# partial write-through: the first 8 of the 16 result stores of the P2/P7/P8/P10 epilogues use sc0 sc1 so half of each tile streams to memory before the seam; later stores stay write-back
# speedup vs baseline: 1.0017x; 1.0017x over previous
; __device__ __forceinline__ unsigned cvtpk(float lo, float hi) { f32x2_t v = {lo, hi}; bf16x2_t b = __builtin_convertvector(v, bf16x2_t); return __builtin_bit_cast(unsigned, b); }
; __device__ __forceinline__ float bflo(unsigned w) { return __uint_as_float(w << 16); }
; __device__ __forceinline__ float bfhi(unsigned w) { return __uint_as_float(w & 0xffff0000u); }
;     __device__ __forceinline__ void operator()(const f32x4 (&acc)[2][2][4][2], const Unit& u, int wr, int wc, int fr, int fq) const {
;     ...
;                 const int row = row0 + ai * 128 + m * 16; float s = 0.f;
; #pragma unroll
;                 for (int bj = 0; bj < 2; ++bj) {
;                     const size_t off = (size_t)row * D + col0 + bj * 128;
;                     f32x4 b0, b1;
;                     if (BASE_F32) { b0 = __builtin_nontemporal_load((const f32x4*)(base + off)); b1 = __builtin_nontemporal_load((const f32x4*)(base + off + 4)); }
;                     else { const u32x4 w = *(const u32x4*)(xb + off); b0 = (f32x4){bflo(w.x), bfhi(w.x), bflo(w.y), bfhi(w.y)}; b1 = (f32x4){bflo(w.z), bfhi(w.z), bflo(w.w), bfhi(w.w)}; }
;                     const f32x4 h0 = b0 + acc[ai][bj][m][0] * scale, h1 = b1 + acc[ai][bj][m][1] * scale;
;                     if (OUT_F32) { *(f32x4*)(out + off) = h0; *(f32x4*)(out + off + 4) = h1; }
;                     else { u32x4 w; w.x = cvtpk(h0[0], h0[1]); w.y = cvtpk(h0[2], h0[3]); w.z = cvtpk(h1[0], h1[1]); w.w = cvtpk(h1[2], h1[3]); st16(xb + off, w); }
;                     s += (h0[0] * h0[0] + h0[1] * h0[1]) + (h0[2] * h0[2] + h0[3] * h0[3]) + (h1[0] * h1[0] + h1[1] * h1[1]) + (h1[2] * h1[2] + h1[3] * h1[3]);
;                 }
;                 s += __shfl_xor(s, 16); s += __shfl_xor(s, 32);
;                 if (fq == 0) __hip_atomic_fetch_add(ssq_out + row, s, __ATOMIC_RELAXED, __HIP_MEMORY_SCOPE_AGENT);
.LBB0_611:
	v_and_b32_e32 v147, 64, v156
	v_xor_b32_e32 v146, 16, v156
	v_add_u32_e32 v147, 64, v147
	v_cmp_lt_i32_e32 vcc, v146, v147
	v_lshl_add_u32 v148, s33, 8, v150
	s_lshl_b32 s26, s52, 8
	v_cndmask_b32_e32 v146, v156, v146, vcc
	v_lshlrev_b32_e32 v158, 2, v146
	v_xor_b32_e32 v146, 32, v156
	v_cmp_lt_i32_e32 vcc, v146, v147
	s_and_b32 s26, s26, 0x700
	v_ashrrev_i32_e32 v149, 31, v148
	v_cndmask_b32_e32 v146, v156, v146, vcc
	v_or_b32_e32 v159, s26, v152
	v_lshlrev_b32_e32 v157, 2, v146
	v_lshlrev_b64 v[146:147], 11, v[148:149]
	v_or_b32_e32 v146, v146, v159
	v_lshl_add_u64 v[168:169], v[146:147], 2, s[68:69]
	global_load_dwordx4 v[172:175], v[168:169], off offset:16 nt
	global_load_dwordx4 v[176:179], v[168:169], off nt
	global_load_dwordx4 v[180:183], v[168:169], off offset:528 nt
	global_load_dwordx4 v[184:187], v[168:169], off offset:512 nt
	s_mov_b64 s[100:101], 0x20000
	v_lshl_add_u64 v[170:171], v[168:169], 0, s[100:101]
	global_load_dwordx4 v[192:195], v[170:171], off offset:16 nt
	global_load_dwordx4 v[196:199], v[170:171], off nt
	global_load_dwordx4 v[200:203], v[170:171], off offset:528 nt
	global_load_dwordx4 v[204:207], v[170:171], off offset:512 nt
	s_mov_b64 s[100:101], 0x40000
	v_lshl_add_u64 v[170:171], v[168:169], 0, s[100:101]
	global_load_dwordx4 v[208:211], v[170:171], off offset:16 nt
	global_load_dwordx4 v[212:215], v[170:171], off nt
	global_load_dwordx4 v[216:219], v[170:171], off offset:528 nt
	global_load_dwordx4 v[220:223], v[170:171], off offset:512 nt
	s_waitcnt vmcnt(10)
	v_pk_fma_f32 v[162:163], v[124:125], 0.5, v[174:175] op_sel_hi:[1,0,1]
	v_pk_fma_f32 v[128:129], v[128:129], 0.5, v[178:179] op_sel_hi:[1,0,1]
	v_pk_fma_f32 v[126:127], v[126:127], 0.5, v[176:177] op_sel_hi:[1,0,1]
	v_pk_fma_f32 v[160:161], v[122:123], 0.5, v[172:173] op_sel_hi:[1,0,1]
	v_lshlrev_b64 v[164:165], 1, v[146:147]
	v_cvt_pk_bf16_f32 v122, v126, v127
	v_cvt_pk_bf16_f32 v123, v128, v129
	v_cvt_pk_bf16_f32 v124, v160, v161
	v_cvt_pk_bf16_f32 v125, v162, v163
	v_lshl_add_u64 v[166:167], s[36:37], 0, v[164:165]
	global_store_dwordx4 v[166:167], v[122:125], off sc0 sc1
	v_or_b32_e32 v164, 0x100, v164
	s_nop 0
	v_mul_f32_e32 v122, v127, v127
	v_mul_f32_e32 v123, v129, v129
	v_fmac_f32_e32 v122, v126, v126
	v_fmac_f32_e32 v123, v128, v128
	v_add_f32_e32 v122, v122, v123
	v_mul_f32_e32 v123, v161, v161
	v_fmac_f32_e32 v123, v160, v160
	v_add_f32_e32 v122, v123, v122
	v_mul_f32_e32 v123, v163, v163
	v_fmac_f32_e32 v123, v162, v162
	v_add_f32_e32 v160, v123, v122
	s_waitcnt vmcnt(10)
	v_pk_fma_f32 v[124:125], v[116:117], 0.5, v[182:183] op_sel_hi:[1,0,1]
	s_waitcnt vmcnt(9)
	v_pk_fma_f32 v[120:121], v[120:121], 0.5, v[186:187] op_sel_hi:[1,0,1]
	v_pk_fma_f32 v[118:119], v[118:119], 0.5, v[184:185] op_sel_hi:[1,0,1]
	v_pk_fma_f32 v[122:123], v[114:115], 0.5, v[180:181] op_sel_hi:[1,0,1]
	s_mov_b64 s[100:101], 0x60000
	v_lshl_add_u64 v[170:171], v[168:169], 0, s[100:101]
	global_load_dwordx4 v[172:175], v[170:171], off offset:16 nt
	global_load_dwordx4 v[176:179], v[170:171], off nt
	global_load_dwordx4 v[180:183], v[170:171], off offset:528 nt
	global_load_dwordx4 v[184:187], v[170:171], off offset:512 nt
	v_cvt_pk_bf16_f32 v114, v118, v119
	v_cvt_pk_bf16_f32 v115, v120, v121
	v_cvt_pk_bf16_f32 v116, v122, v123
	v_cvt_pk_bf16_f32 v117, v124, v125
	v_lshl_add_u64 v[126:127], s[36:37], 0, v[164:165]
	global_store_dwordx4 v[126:127], v[114:117], off sc0 sc1
	s_nop 1
	v_mul_f32_e32 v114, v119, v119
	v_mul_f32_e32 v115, v121, v121
	v_fmac_f32_e32 v114, v118, v118
	v_fmac_f32_e32 v115, v120, v120
	v_add_f32_e32 v114, v114, v115
	v_mul_f32_e32 v115, v123, v123
	v_fmac_f32_e32 v115, v122, v122
	v_add_f32_e32 v114, v115, v114
	v_mul_f32_e32 v115, v125, v125
	v_fmac_f32_e32 v115, v124, v124
	v_add_f32_e32 v114, v115, v114
	v_add_f32_e32 v114, v160, v114
	ds_bpermute_b32 v115, v158, v114
	s_waitcnt lgkmcnt(0)
	v_add_f32_e32 v116, v114, v115
	ds_bpermute_b32 v117, v157, v116
	v_lshl_add_u64 v[114:115], v[148:149], 2, s[16:17]
	s_and_saveexec_b64 s[26:27], s[0:1]
	s_cbranch_execz .LBB0_613
	s_waitcnt lgkmcnt(0)
	v_add_f32_e32 v116, v116, v117
	global_atomic_add_f32 v[114:115], v116, off
.LBB0_613:
	s_or_b64 exec, exec, s[26:27]
	v_or_b32_e32 v116, 16, v148
	s_waitcnt lgkmcnt(0)
	v_ashrrev_i32_e32 v117, 31, v116
	v_lshlrev_b64 v[124:125], 11, v[116:117]
	v_or_b32_e32 v124, v124, v159
	v_lshl_add_u64 v[126:127], v[124:125], 2, s[68:69]
	s_waitcnt vmcnt(13)
	v_pk_fma_f32 v[118:119], v[108:109], 0.5, v[194:195] op_sel_hi:[1,0,1]
	s_waitcnt vmcnt(12)
	v_pk_fma_f32 v[112:113], v[112:113], 0.5, v[198:199] op_sel_hi:[1,0,1]
	v_pk_fma_f32 v[110:111], v[110:111], 0.5, v[196:197] op_sel_hi:[1,0,1]
	v_pk_fma_f32 v[116:117], v[106:107], 0.5, v[192:193] op_sel_hi:[1,0,1]
	v_lshlrev_b64 v[120:121], 1, v[124:125]
	v_cvt_pk_bf16_f32 v106, v110, v111
	v_cvt_pk_bf16_f32 v107, v112, v113
	v_cvt_pk_bf16_f32 v108, v116, v117
	v_cvt_pk_bf16_f32 v109, v118, v119
	v_lshl_add_u64 v[122:123], s[36:37], 0, v[120:121]
	global_store_dwordx4 v[122:123], v[106:109], off sc0 sc1
	v_or_b32_e32 v120, 0x100, v120
	s_nop 0
	v_mul_f32_e32 v106, v111, v111
	v_mul_f32_e32 v107, v113, v113
	v_fmac_f32_e32 v106, v110, v110
	v_fmac_f32_e32 v107, v112, v112
	v_add_f32_e32 v106, v106, v107
	v_mul_f32_e32 v107, v117, v117
	v_fmac_f32_e32 v107, v116, v116
	v_add_f32_e32 v106, v107, v106
	v_mul_f32_e32 v107, v119, v119
	v_fmac_f32_e32 v107, v118, v118
	v_add_f32_e32 v116, v107, v106
	s_waitcnt vmcnt(12)
	v_pk_fma_f32 v[108:109], v[100:101], 0.5, v[202:203] op_sel_hi:[1,0,1]
	s_waitcnt vmcnt(11)
	v_pk_fma_f32 v[104:105], v[104:105], 0.5, v[206:207] op_sel_hi:[1,0,1]
	v_pk_fma_f32 v[102:103], v[102:103], 0.5, v[204:205] op_sel_hi:[1,0,1]
	v_pk_fma_f32 v[106:107], v[98:99], 0.5, v[200:201] op_sel_hi:[1,0,1]
	s_mov_b64 s[100:101], 0x100000
	v_lshl_add_u64 v[170:171], v[168:169], 0, s[100:101]
	global_load_dwordx4 v[192:195], v[170:171], off offset:16 nt
	global_load_dwordx4 v[196:199], v[170:171], off nt
	global_load_dwordx4 v[200:203], v[170:171], off offset:528 nt
	global_load_dwordx4 v[204:207], v[170:171], off offset:512 nt
	v_cvt_pk_bf16_f32 v98, v102, v103
	v_cvt_pk_bf16_f32 v99, v104, v105
	v_cvt_pk_bf16_f32 v100, v106, v107
	v_cvt_pk_bf16_f32 v101, v108, v109
	v_lshl_add_u64 v[110:111], s[36:37], 0, v[120:121]
	global_store_dwordx4 v[110:111], v[98:101], off sc0 sc1
	s_nop 1
	v_mul_f32_e32 v98, v103, v103
	v_mul_f32_e32 v99, v105, v105
	v_fmac_f32_e32 v98, v102, v102
	v_fmac_f32_e32 v99, v104, v104
	v_add_f32_e32 v98, v98, v99
	v_mul_f32_e32 v99, v107, v107
	v_fmac_f32_e32 v99, v106, v106
	v_add_f32_e32 v98, v99, v98
	v_mul_f32_e32 v99, v109, v109
	v_fmac_f32_e32 v99, v108, v108
	v_add_f32_e32 v98, v99, v98
	v_add_f32_e32 v98, v116, v98
	ds_bpermute_b32 v99, v158, v98
	s_waitcnt lgkmcnt(0)
	v_add_f32_e32 v98, v98, v99
	ds_bpermute_b32 v99, v157, v98
	s_and_saveexec_b64 s[26:27], s[0:1]
	s_cbranch_execz .LBB0_615
	s_waitcnt lgkmcnt(0)
	v_add_f32_e32 v98, v98, v99
	global_atomic_add_f32 v[114:115], v98, off offset:64
; __device__ __forceinline__ unsigned cvtpk(float lo, float hi) { f32x2_t v = {lo, hi}; bf16x2_t b = __builtin_convertvector(v, bf16x2_t); return __builtin_bit_cast(unsigned, b); }
; __device__ __forceinline__ float bflo(unsigned w) { return __uint_as_float(w << 16); }
; __device__ __forceinline__ float bfhi(unsigned w) { return __uint_as_float(w & 0xffff0000u); }
;     __device__ __forceinline__ void operator()(const f32x4 (&acc)[2][2][4][2], const Unit& u, int wr, int wc, int fr, int fq) const {
;     ...
;                 const int row = row0 + ai * 128 + m * 16; float s = 0.f;
; #pragma unroll
;                 for (int bj = 0; bj < 2; ++bj) {
;                     const size_t off = (size_t)row * D + col0 + bj * 128;
;                     f32x4 b0, b1;
;                     if (BASE_F32) { b0 = __builtin_nontemporal_load((const f32x4*)(base + off)); b1 = __builtin_nontemporal_load((const f32x4*)(base + off + 4)); }
;                     else { const u32x4 w = *(const u32x4*)(xb + off); b0 = (f32x4){bflo(w.x), bfhi(w.x), bflo(w.y), bfhi(w.y)}; b1 = (f32x4){bflo(w.z), bfhi(w.z), bflo(w.w), bfhi(w.w)}; }
;                     const f32x4 h0 = b0 + acc[ai][bj][m][0] * scale, h1 = b1 + acc[ai][bj][m][1] * scale;
;                     if (OUT_F32) { *(f32x4*)(out + off) = h0; *(f32x4*)(out + off + 4) = h1; }
;                     else { u32x4 w; w.x = cvtpk(h0[0], h0[1]); w.y = cvtpk(h0[2], h0[3]); w.z = cvtpk(h1[0], h1[1]); w.w = cvtpk(h1[2], h1[3]); st16(xb + off, w); }
;                     s += (h0[0] * h0[0] + h0[1] * h0[1]) + (h0[2] * h0[2] + h0[3] * h0[3]) + (h1[0] * h1[0] + h1[1] * h1[1]) + (h1[2] * h1[2] + h1[3] * h1[3]);
;                 }
;                 s += __shfl_xor(s, 16); s += __shfl_xor(s, 32);
;                 if (fq == 0) __hip_atomic_fetch_add(ssq_out + row, s, __ATOMIC_RELAXED, __HIP_MEMORY_SCOPE_AGENT);
.LBB0_615:
	s_or_b64 exec, exec, s[26:27]
	v_or_b32_e32 v98, 32, v148
	s_waitcnt lgkmcnt(0)
	v_ashrrev_i32_e32 v99, 31, v98
	v_lshlrev_b64 v[106:107], 11, v[98:99]
	v_or_b32_e32 v106, v106, v159
	v_lshl_add_u64 v[108:109], v[106:107], 2, s[68:69]
	s_waitcnt vmcnt(15)
	v_pk_fma_f32 v[100:101], v[92:93], 0.5, v[210:211] op_sel_hi:[1,0,1]
	s_waitcnt vmcnt(14)
	v_pk_fma_f32 v[96:97], v[96:97], 0.5, v[214:215] op_sel_hi:[1,0,1]
	v_pk_fma_f32 v[94:95], v[94:95], 0.5, v[212:213] op_sel_hi:[1,0,1]
	v_pk_fma_f32 v[98:99], v[90:91], 0.5, v[208:209] op_sel_hi:[1,0,1]
	v_lshlrev_b64 v[102:103], 1, v[106:107]
	v_cvt_pk_bf16_f32 v90, v94, v95
	v_cvt_pk_bf16_f32 v91, v96, v97
	v_cvt_pk_bf16_f32 v92, v98, v99
	v_cvt_pk_bf16_f32 v93, v100, v101
	v_lshl_add_u64 v[104:105], s[36:37], 0, v[102:103]
	global_store_dwordx4 v[104:105], v[90:93], off sc0 sc1
	v_or_b32_e32 v102, 0x100, v102
	s_nop 0
	v_mul_f32_e32 v90, v95, v95
	v_mul_f32_e32 v91, v97, v97
	v_fmac_f32_e32 v90, v94, v94
	v_fmac_f32_e32 v91, v96, v96
	v_add_f32_e32 v90, v90, v91
	v_mul_f32_e32 v91, v99, v99
	v_fmac_f32_e32 v91, v98, v98
	v_add_f32_e32 v90, v91, v90
	v_mul_f32_e32 v91, v101, v101
	v_fmac_f32_e32 v91, v100, v100
	v_add_f32_e32 v98, v91, v90
	s_waitcnt vmcnt(14)
	v_pk_fma_f32 v[92:93], v[84:85], 0.5, v[218:219] op_sel_hi:[1,0,1]
	s_waitcnt vmcnt(13)
	v_pk_fma_f32 v[88:89], v[88:89], 0.5, v[222:223] op_sel_hi:[1,0,1]
	v_pk_fma_f32 v[86:87], v[86:87], 0.5, v[220:221] op_sel_hi:[1,0,1]
	v_pk_fma_f32 v[90:91], v[82:83], 0.5, v[216:217] op_sel_hi:[1,0,1]
	s_mov_b64 s[100:101], 0x120000
	v_lshl_add_u64 v[170:171], v[168:169], 0, s[100:101]
	global_load_dwordx4 v[208:211], v[170:171], off offset:16 nt
	global_load_dwordx4 v[212:215], v[170:171], off nt
	global_load_dwordx4 v[216:219], v[170:171], off offset:528 nt
	global_load_dwordx4 v[220:223], v[170:171], off offset:512 nt
	v_cvt_pk_bf16_f32 v82, v86, v87
	v_cvt_pk_bf16_f32 v83, v88, v89
	v_cvt_pk_bf16_f32 v84, v90, v91
	v_cvt_pk_bf16_f32 v85, v92, v93
	v_lshl_add_u64 v[94:95], s[36:37], 0, v[102:103]
	global_store_dwordx4 v[94:95], v[82:85], off sc0 sc1
	s_nop 1
	v_mul_f32_e32 v82, v87, v87
	v_mul_f32_e32 v83, v89, v89
	v_fmac_f32_e32 v82, v86, v86
	v_fmac_f32_e32 v83, v88, v88
	v_add_f32_e32 v82, v82, v83
	v_mul_f32_e32 v83, v91, v91
	v_fmac_f32_e32 v83, v90, v90
	v_add_f32_e32 v82, v83, v82
	v_mul_f32_e32 v83, v93, v93
	v_fmac_f32_e32 v83, v92, v92
	v_add_f32_e32 v82, v83, v82
	v_add_f32_e32 v82, v98, v82
	ds_bpermute_b32 v83, v158, v82
	s_waitcnt lgkmcnt(0)
	v_add_f32_e32 v82, v82, v83
	ds_bpermute_b32 v83, v157, v82
	s_and_saveexec_b64 s[26:27], s[0:1]
	s_cbranch_execz .LBB0_617
	s_waitcnt lgkmcnt(0)
	v_add_f32_e32 v82, v82, v83
	global_atomic_add_f32 v[114:115], v82, off offset:128
.LBB0_617:
	s_or_b64 exec, exec, s[26:27]
	v_or_b32_e32 v82, 48, v148
	s_waitcnt lgkmcnt(0)
	v_ashrrev_i32_e32 v83, 31, v82
	v_lshlrev_b64 v[90:91], 11, v[82:83]
	v_or_b32_e32 v90, v90, v159
	v_lshl_add_u64 v[92:93], v[90:91], 2, s[68:69]
	s_waitcnt vmcnt(16)
	v_pk_fma_f32 v[84:85], v[76:77], 0.5, v[174:175] op_sel_hi:[1,0,1]
	s_waitcnt vmcnt(15)
	v_pk_fma_f32 v[80:81], v[80:81], 0.5, v[178:179] op_sel_hi:[1,0,1]
	v_pk_fma_f32 v[78:79], v[78:79], 0.5, v[176:177] op_sel_hi:[1,0,1]
	v_pk_fma_f32 v[82:83], v[74:75], 0.5, v[172:173] op_sel_hi:[1,0,1]
	v_lshlrev_b64 v[86:87], 1, v[90:91]
	v_cvt_pk_bf16_f32 v74, v78, v79
	v_cvt_pk_bf16_f32 v75, v80, v81
	v_cvt_pk_bf16_f32 v76, v82, v83
	v_cvt_pk_bf16_f32 v77, v84, v85
	v_lshl_add_u64 v[88:89], s[36:37], 0, v[86:87]
	global_store_dwordx4 v[88:89], v[74:77], off sc0 sc1
	v_or_b32_e32 v86, 0x100, v86
	s_nop 0
	v_mul_f32_e32 v74, v79, v79
	v_mul_f32_e32 v75, v81, v81
	v_fmac_f32_e32 v74, v78, v78
	v_fmac_f32_e32 v75, v80, v80
	v_add_f32_e32 v74, v74, v75
	v_mul_f32_e32 v75, v83, v83
	v_fmac_f32_e32 v75, v82, v82
	v_add_f32_e32 v74, v75, v74
	v_mul_f32_e32 v75, v85, v85
	v_fmac_f32_e32 v75, v84, v84
	v_add_f32_e32 v82, v75, v74
	s_waitcnt vmcnt(15)
	v_pk_fma_f32 v[76:77], v[68:69], 0.5, v[182:183] op_sel_hi:[1,0,1]
	s_waitcnt vmcnt(14)
	v_pk_fma_f32 v[72:73], v[72:73], 0.5, v[186:187] op_sel_hi:[1,0,1]
	v_pk_fma_f32 v[70:71], v[70:71], 0.5, v[184:185] op_sel_hi:[1,0,1]
	v_pk_fma_f32 v[74:75], v[66:67], 0.5, v[180:181] op_sel_hi:[1,0,1]
	s_mov_b64 s[100:101], 0x140000
	v_lshl_add_u64 v[170:171], v[168:169], 0, s[100:101]
	global_load_dwordx4 v[172:175], v[170:171], off offset:16 nt
	global_load_dwordx4 v[176:179], v[170:171], off nt
	global_load_dwordx4 v[180:183], v[170:171], off offset:528 nt
	global_load_dwordx4 v[184:187], v[170:171], off offset:512 nt
	v_cvt_pk_bf16_f32 v66, v70, v71
	v_cvt_pk_bf16_f32 v67, v72, v73
	v_cvt_pk_bf16_f32 v68, v74, v75
	v_cvt_pk_bf16_f32 v69, v76, v77
	v_lshl_add_u64 v[78:79], s[36:37], 0, v[86:87]
	global_store_dwordx4 v[78:79], v[66:69], off sc0 sc1
	s_nop 1
	v_mul_f32_e32 v66, v71, v71
	v_mul_f32_e32 v67, v73, v73
	v_fmac_f32_e32 v66, v70, v70
	v_fmac_f32_e32 v67, v72, v72
	v_add_f32_e32 v66, v66, v67
	v_mul_f32_e32 v67, v75, v75
	v_fmac_f32_e32 v67, v74, v74
	v_add_f32_e32 v66, v67, v66
	v_mul_f32_e32 v67, v77, v77
	v_fmac_f32_e32 v67, v76, v76
	v_add_f32_e32 v66, v67, v66
	v_add_f32_e32 v66, v82, v66
	ds_bpermute_b32 v67, v158, v66
	s_waitcnt lgkmcnt(0)
	v_add_f32_e32 v66, v66, v67
	ds_bpermute_b32 v67, v157, v66
	s_and_saveexec_b64 s[26:27], s[0:1]
	s_cbranch_execz .LBB0_619
	s_waitcnt lgkmcnt(0)
	v_add_f32_e32 v66, v66, v67
	global_atomic_add_f32 v[114:115], v66, off offset:192

; __device__ __forceinline__ unsigned cvtpk(float lo, float hi) { f32x2_t v = {lo, hi}; bf16x2_t b = __builtin_convertvector(v, bf16x2_t); return __builtin_bit_cast(unsigned, b); }
; __device__ __forceinline__ float bflo(unsigned w) { return __uint_as_float(w << 16); }
; __device__ __forceinline__ float bfhi(unsigned w) { return __uint_as_float(w & 0xffff0000u); }
;     __device__ __forceinline__ void operator()(const f32x4 (&acc)[2][2][4][2], const Unit& u, int wr, int wc, int fr, int fq) const {
;     ...
;                 const int row = row0 + ai * 128 + m * 16; float s = 0.f;
; #pragma unroll
;                 for (int bj = 0; bj < 2; ++bj) {
;                     const size_t off = (size_t)row * D + col0 + bj * 128;
;                     f32x4 b0, b1;
;                     if (BASE_F32) { b0 = __builtin_nontemporal_load((const f32x4*)(base + off)); b1 = __builtin_nontemporal_load((const f32x4*)(base + off + 4)); }
;                     else { const u32x4 w = *(const u32x4*)(xb + off); b0 = (f32x4){bflo(w.x), bfhi(w.x), bflo(w.y), bfhi(w.y)}; b1 = (f32x4){bflo(w.z), bfhi(w.z), bflo(w.w), bfhi(w.w)}; }
;                     const f32x4 h0 = b0 + acc[ai][bj][m][0] * scale, h1 = b1 + acc[ai][bj][m][1] * scale;
;                     if (OUT_F32) { *(f32x4*)(out + off) = h0; *(f32x4*)(out + off + 4) = h1; }
;                     else { u32x4 w; w.x = cvtpk(h0[0], h0[1]); w.y = cvtpk(h0[2], h0[3]); w.z = cvtpk(h1[0], h1[1]); w.w = cvtpk(h1[2], h1[3]); st16(xb + off, w); }
;                     s += (h0[0] * h0[0] + h0[1] * h0[1]) + (h0[2] * h0[2] + h0[3] * h0[3]) + (h1[0] * h1[0] + h1[1] * h1[1]) + (h1[2] * h1[2] + h1[3] * h1[3]);
;                 }
;                 s += __shfl_xor(s, 16); s += __shfl_xor(s, 32);
;                 if (fq == 0) __hip_atomic_fetch_add(ssq_out + row, s, __ATOMIC_RELAXED, __HIP_MEMORY_SCOPE_AGENT);
.LBB0_1333:
	v_lshl_add_u32 v148, s24, 8, v152
	s_lshl_b32 s17, s26, 8
	s_and_b32 s17, s17, 0x700
	v_ashrrev_i32_e32 v149, 31, v148
	v_or_b32_e32 v138, s17, v154
	v_lshlrev_b64 v[160:161], 12, v[148:149]
	v_lshl_add_u64 v[160:161], s[36:37], 0, v[160:161]
	v_lshlrev_b32_e32 v138, 1, v138
	v_lshl_add_u64 v[170:171], v[160:161], 0, v[138:139]
	global_load_dwordx4 v[162:165], v[170:171], off
	global_load_dwordx4 v[166:169], v[170:171], off offset:256
	v_or_b32_e32 v182, 16, v148
	v_ashrrev_i32_e32 v183, 31, v182
	v_lshlrev_b64 v[182:183], 12, v[182:183]
	v_lshl_add_u64 v[182:183], s[36:37], 0, v[182:183]
	v_lshl_add_u64 v[182:183], v[182:183], 0, v[138:139]
	global_load_dwordx4 v[184:187], v[182:183], off
	global_load_dwordx4 v[192:195], v[182:183], off offset:256
	v_or_b32_e32 v182, 32, v148
	v_ashrrev_i32_e32 v183, 31, v182
	v_lshlrev_b64 v[182:183], 12, v[182:183]
	v_lshl_add_u64 v[182:183], s[36:37], 0, v[182:183]
	v_lshl_add_u64 v[182:183], v[182:183], 0, v[138:139]
	global_load_dwordx4 v[196:199], v[182:183], off
	global_load_dwordx4 v[200:203], v[182:183], off offset:256
	v_or_b32_e32 v182, 48, v148
	v_ashrrev_i32_e32 v183, 31, v182
	v_lshlrev_b64 v[182:183], 12, v[182:183]
	v_lshl_add_u64 v[182:183], s[36:37], 0, v[182:183]
	v_lshl_add_u64 v[182:183], v[182:183], 0, v[138:139]
	global_load_dwordx4 v[204:207], v[182:183], off
	global_load_dwordx4 v[208:211], v[182:183], off offset:256
	v_add_u32_e32 v182, 0x80, v148
	v_ashrrev_i32_e32 v183, 31, v182
	v_lshlrev_b64 v[182:183], 12, v[182:183]
	v_lshl_add_u64 v[182:183], s[36:37], 0, v[182:183]
	v_lshl_add_u64 v[182:183], v[182:183], 0, v[138:139]
	global_load_dwordx4 v[212:215], v[182:183], off
	global_load_dwordx4 v[216:219], v[182:183], off offset:256
	v_add_u32_e32 v182, 0x90, v148
	v_ashrrev_i32_e32 v183, 31, v182
	v_lshlrev_b64 v[182:183], 12, v[182:183]
	v_lshl_add_u64 v[182:183], s[36:37], 0, v[182:183]
	v_lshl_add_u64 v[182:183], v[182:183], 0, v[138:139]
	global_load_dwordx4 v[220:223], v[182:183], off
	global_load_dwordx4 v[224:227], v[182:183], off offset:256
	v_add_u32_e32 v182, 0xa0, v148
	v_ashrrev_i32_e32 v183, 31, v182
	v_lshlrev_b64 v[182:183], 12, v[182:183]
	v_lshl_add_u64 v[182:183], s[36:37], 0, v[182:183]
	v_lshl_add_u64 v[182:183], v[182:183], 0, v[138:139]
	global_load_dwordx4 v[228:231], v[182:183], off
	global_load_dwordx4 v[232:235], v[182:183], off offset:256
	v_and_b32_e32 v160, 64, v158
	v_xor_b32_e32 v159, 16, v158
	v_add_u32_e32 v160, 64, v160
	v_xor_b32_e32 v161, 32, v158
	v_cmp_lt_i32_e32 vcc, v159, v160
	s_waitcnt vmcnt(12)
	v_lshlrev_b32_e32 v172, 16, v162
	v_cndmask_b32_e32 v159, v158, v159, vcc
	v_cmp_lt_i32_e32 vcc, v161, v160
	v_and_b32_e32 v173, 0xffff0000, v162
	v_lshlrev_b32_e32 v162, 16, v163
	v_and_b32_e32 v163, 0xffff0000, v163
	v_lshlrev_b32_e32 v176, 16, v166
	v_and_b32_e32 v177, 0xffff0000, v166
	v_lshlrev_b32_e32 v166, 16, v167
	v_and_b32_e32 v167, 0xffff0000, v167
	v_cndmask_b32_e32 v161, v158, v161, vcc
	v_lshlrev_b32_e32 v174, 16, v164
	v_and_b32_e32 v175, 0xffff0000, v164
	v_lshlrev_b32_e32 v164, 16, v165
	v_and_b32_e32 v165, 0xffff0000, v165
	v_lshlrev_b32_e32 v180, 16, v168
	v_and_b32_e32 v181, 0xffff0000, v168
	v_lshlrev_b32_e32 v168, 16, v169
	v_and_b32_e32 v169, 0xffff0000, v169
	v_pk_add_f32 v[128:129], v[128:129], v[162:163]
	v_pk_add_f32 v[126:127], v[126:127], v[172:173]
	v_pk_add_f32 v[120:121], v[120:121], v[166:167]
	v_pk_add_f32 v[118:119], v[118:119], v[176:177]
	v_lshlrev_b32_e32 v160, 2, v159
	v_lshlrev_b32_e32 v159, 2, v161
	v_pk_add_f32 v[124:125], v[124:125], v[164:165]
	v_pk_add_f32 v[122:123], v[122:123], v[174:175]
	v_pk_add_f32 v[162:163], v[116:117], v[168:169]
	v_pk_add_f32 v[164:165], v[114:115], v[180:181]
	v_mul_f32_e32 v116, v127, v127
	v_mul_f32_e32 v117, v129, v129
	v_mul_f32_e32 v161, v119, v119
	v_mul_f32_e32 v166, v121, v121
	v_cvt_pk_bf16_f32 v114, v126, v127
	v_mul_f32_e32 v127, v123, v123
	v_mul_f32_e32 v167, v165, v165
	v_fmac_f32_e32 v116, v126, v126
	v_fmac_f32_e32 v117, v128, v128
	v_fmac_f32_e32 v161, v118, v118
	v_fmac_f32_e32 v166, v120, v120
	v_cvt_pk_bf16_f32 v115, v128, v129
	v_mul_f32_e32 v129, v125, v125
	v_mul_f32_e32 v168, v163, v163
	v_fmac_f32_e32 v127, v122, v122
	v_fmac_f32_e32 v167, v164, v164
	v_add_f32_e32 v116, v116, v117
	v_add_f32_e32 v117, v161, v166
	v_fmac_f32_e32 v129, v124, v124
	v_fmac_f32_e32 v168, v162, v162
	v_add_f32_e32 v116, v127, v116
	v_add_f32_e32 v117, v167, v117
	v_add_f32_e32 v116, v129, v116
	v_add_f32_e32 v117, v168, v117
	v_add_f32_e32 v126, v116, v117
	ds_bpermute_b32 v127, v160, v126
	v_cvt_pk_bf16_f32 v116, v122, v123
	v_cvt_pk_bf16_f32 v117, v124, v125
	global_store_dwordx4 v[170:171], v[114:117], off sc0 sc1
	s_waitcnt lgkmcnt(0)
	s_nop 0
	v_add_f32_e32 v114, v126, v127
	ds_bpermute_b32 v115, v159, v114
	v_cvt_pk_bf16_f32 v116, v118, v119
	v_cvt_pk_bf16_f32 v117, v120, v121
	v_cvt_pk_bf16_f32 v118, v164, v165
	v_cvt_pk_bf16_f32 v119, v162, v163
	global_store_dwordx4 v[170:171], v[116:119], off offset:256 sc0 sc1
	s_and_saveexec_b64 s[24:25], s[2:3]
	s_cbranch_execz .LBB0_1335
	v_lshl_add_u64 v[116:117], v[148:149], 2, s[6:7]
	s_waitcnt lgkmcnt(0)
	v_add_f32_e32 v114, v114, v115
	global_atomic_add_f32 v[116:117], v114, off
; __device__ __forceinline__ unsigned cvtpk(float lo, float hi) { f32x2_t v = {lo, hi}; bf16x2_t b = __builtin_convertvector(v, bf16x2_t); return __builtin_bit_cast(unsigned, b); }
; __device__ __forceinline__ float bflo(unsigned w) { return __uint_as_float(w << 16); }
; __device__ __forceinline__ float bfhi(unsigned w) { return __uint_as_float(w & 0xffff0000u); }
;     __device__ __forceinline__ void operator()(const f32x4 (&acc)[2][2][4][2], const Unit& u, int wr, int wc, int fr, int fq) const {
;     ...
;                 const int row = row0 + ai * 128 + m * 16; float s = 0.f;
; #pragma unroll
;                 for (int bj = 0; bj < 2; ++bj) {
;                     const size_t off = (size_t)row * D + col0 + bj * 128;
;                     f32x4 b0, b1;
;                     if (BASE_F32) { b0 = __builtin_nontemporal_load((const f32x4*)(base + off)); b1 = __builtin_nontemporal_load((const f32x4*)(base + off + 4)); }
;                     else { const u32x4 w = *(const u32x4*)(xb + off); b0 = (f32x4){bflo(w.x), bfhi(w.x), bflo(w.y), bfhi(w.y)}; b1 = (f32x4){bflo(w.z), bfhi(w.z), bflo(w.w), bfhi(w.w)}; }
;                     const f32x4 h0 = b0 + acc[ai][bj][m][0] * scale, h1 = b1 + acc[ai][bj][m][1] * scale;
;                     if (OUT_F32) { *(f32x4*)(out + off) = h0; *(f32x4*)(out + off + 4) = h1; }
;                     else { u32x4 w; w.x = cvtpk(h0[0], h0[1]); w.y = cvtpk(h0[2], h0[3]); w.z = cvtpk(h1[0], h1[1]); w.w = cvtpk(h1[2], h1[3]); st16(xb + off, w); }
;                     s += (h0[0] * h0[0] + h0[1] * h0[1]) + (h0[2] * h0[2] + h0[3] * h0[3]) + (h1[0] * h1[0] + h1[1] * h1[1]) + (h1[2] * h1[2] + h1[3] * h1[3]);
;                 }
;                 s += __shfl_xor(s, 16); s += __shfl_xor(s, 32);
;                 if (fq == 0) __hip_atomic_fetch_add(ssq_out + row, s, __ATOMIC_RELAXED, __HIP_MEMORY_SCOPE_AGENT);
.LBB0_1335:
	s_or_b64 exec, exec, s[24:25]
	v_or_b32_e32 v114, 16, v148
	s_waitcnt lgkmcnt(0)
	v_ashrrev_i32_e32 v115, 31, v114
	v_lshlrev_b64 v[116:117], 12, v[114:115]
	v_lshl_add_u64 v[116:117], s[36:37], 0, v[116:117]
	v_lshl_add_u64 v[124:125], v[116:117], 0, v[138:139]
	s_waitcnt vmcnt(13)
	v_lshlrev_b32_e32 v126, 16, v184
	v_and_b32_e32 v127, 0xffff0000, v184
	v_lshlrev_b32_e32 v116, 16, v185
	v_and_b32_e32 v117, 0xffff0000, v185
	s_waitcnt vmcnt(12)
	v_lshlrev_b32_e32 v162, 16, v192
	v_and_b32_e32 v163, 0xffff0000, v192
	v_lshlrev_b32_e32 v120, 16, v193
	v_and_b32_e32 v121, 0xffff0000, v193
	v_lshlrev_b32_e32 v128, 16, v186
	v_and_b32_e32 v129, 0xffff0000, v186
	v_lshlrev_b32_e32 v118, 16, v187
	v_and_b32_e32 v119, 0xffff0000, v187
	v_lshlrev_b32_e32 v164, 16, v194
	v_and_b32_e32 v165, 0xffff0000, v194
	v_lshlrev_b32_e32 v122, 16, v195
	v_and_b32_e32 v123, 0xffff0000, v195
	v_add_u32_e32 v182, 0xb0, v148
	v_ashrrev_i32_e32 v183, 31, v182
	v_lshlrev_b64 v[182:183], 12, v[182:183]
	v_lshl_add_u64 v[182:183], s[36:37], 0, v[182:183]
	v_lshl_add_u64 v[182:183], v[182:183], 0, v[138:139]
	global_load_dwordx4 v[184:187], v[182:183], off
	global_load_dwordx4 v[192:195], v[182:183], off offset:256
	v_pk_add_f32 v[112:113], v[112:113], v[116:117]
	v_pk_add_f32 v[110:111], v[110:111], v[126:127]
	v_pk_add_f32 v[104:105], v[104:105], v[120:121]
	v_pk_add_f32 v[102:103], v[102:103], v[162:163]
	v_pk_add_f32 v[108:109], v[108:109], v[118:119]
	v_pk_add_f32 v[106:107], v[106:107], v[128:129]
	v_pk_add_f32 v[116:117], v[100:101], v[122:123]
	v_pk_add_f32 v[118:119], v[98:99], v[164:165]
	v_mul_f32_e32 v100, v111, v111
	v_mul_f32_e32 v101, v113, v113
	v_mul_f32_e32 v120, v103, v103
	v_mul_f32_e32 v121, v105, v105
	v_cvt_pk_bf16_f32 v98, v110, v111
	v_mul_f32_e32 v111, v107, v107
	v_mul_f32_e32 v122, v119, v119
	v_fmac_f32_e32 v100, v110, v110
	v_fmac_f32_e32 v101, v112, v112
	v_fmac_f32_e32 v120, v102, v102
	v_fmac_f32_e32 v121, v104, v104
	v_cvt_pk_bf16_f32 v99, v112, v113
	v_mul_f32_e32 v113, v109, v109
	v_mul_f32_e32 v123, v117, v117
	v_fmac_f32_e32 v111, v106, v106
	v_fmac_f32_e32 v122, v118, v118
	v_add_f32_e32 v100, v100, v101
	v_add_f32_e32 v101, v120, v121
	v_fmac_f32_e32 v113, v108, v108
	v_fmac_f32_e32 v123, v116, v116
	v_add_f32_e32 v100, v111, v100
	v_add_f32_e32 v101, v122, v101
	v_add_f32_e32 v100, v113, v100
	v_add_f32_e32 v101, v123, v101
	v_add_f32_e32 v110, v100, v101
	ds_bpermute_b32 v111, v160, v110
	v_cvt_pk_bf16_f32 v100, v106, v107
	v_cvt_pk_bf16_f32 v101, v108, v109
	global_store_dwordx4 v[124:125], v[98:101], off sc0 sc1
	s_waitcnt lgkmcnt(0)
	s_nop 0
	v_add_f32_e32 v98, v110, v111
	ds_bpermute_b32 v99, v159, v98
	v_cvt_pk_bf16_f32 v100, v102, v103
	v_cvt_pk_bf16_f32 v101, v104, v105
	v_cvt_pk_bf16_f32 v102, v118, v119
	v_cvt_pk_bf16_f32 v103, v116, v117
	global_store_dwordx4 v[124:125], v[100:103], off offset:256 sc0 sc1
	s_and_saveexec_b64 s[24:25], s[2:3]
	s_cbranch_execz .LBB0_1337
	v_lshl_add_u64 v[100:101], v[114:115], 2, s[6:7]
	s_waitcnt lgkmcnt(0)
	v_add_f32_e32 v98, v98, v99
	global_atomic_add_f32 v[100:101], v98, off
; __device__ __forceinline__ unsigned cvtpk(float lo, float hi) { f32x2_t v = {lo, hi}; bf16x2_t b = __builtin_convertvector(v, bf16x2_t); return __builtin_bit_cast(unsigned, b); }
; __device__ __forceinline__ float bflo(unsigned w) { return __uint_as_float(w << 16); }
; __device__ __forceinline__ float bfhi(unsigned w) { return __uint_as_float(w & 0xffff0000u); }
;     __device__ __forceinline__ void operator()(const f32x4 (&acc)[2][2][4][2], const Unit& u, int wr, int wc, int fr, int fq) const {
;     ...
;                 const int row = row0 + ai * 128 + m * 16; float s = 0.f;
; #pragma unroll
;                 for (int bj = 0; bj < 2; ++bj) {
;                     const size_t off = (size_t)row * D + col0 + bj * 128;
;                     f32x4 b0, b1;
;                     if (BASE_F32) { b0 = __builtin_nontemporal_load((const f32x4*)(base + off)); b1 = __builtin_nontemporal_load((const f32x4*)(base + off + 4)); }
;                     else { const u32x4 w = *(const u32x4*)(xb + off); b0 = (f32x4){bflo(w.x), bfhi(w.x), bflo(w.y), bfhi(w.y)}; b1 = (f32x4){bflo(w.z), bfhi(w.z), bflo(w.w), bfhi(w.w)}; }
;                     const f32x4 h0 = b0 + acc[ai][bj][m][0] * scale, h1 = b1 + acc[ai][bj][m][1] * scale;
;                     if (OUT_F32) { *(f32x4*)(out + off) = h0; *(f32x4*)(out + off + 4) = h1; }
;                     else { u32x4 w; w.x = cvtpk(h0[0], h0[1]); w.y = cvtpk(h0[2], h0[3]); w.z = cvtpk(h1[0], h1[1]); w.w = cvtpk(h1[2], h1[3]); st16(xb + off, w); }
;                     s += (h0[0] * h0[0] + h0[1] * h0[1]) + (h0[2] * h0[2] + h0[3] * h0[3]) + (h1[0] * h1[0] + h1[1] * h1[1]) + (h1[2] * h1[2] + h1[3] * h1[3]);
;                 }
;                 s += __shfl_xor(s, 16); s += __shfl_xor(s, 32);
;                 if (fq == 0) __hip_atomic_fetch_add(ssq_out + row, s, __ATOMIC_RELAXED, __HIP_MEMORY_SCOPE_AGENT);
.LBB0_1337:
	s_or_b64 exec, exec, s[24:25]
	v_or_b32_e32 v98, 32, v148
	s_waitcnt lgkmcnt(0)
	v_ashrrev_i32_e32 v99, 31, v98
	v_lshlrev_b64 v[100:101], 12, v[98:99]
	v_lshl_add_u64 v[100:101], s[36:37], 0, v[100:101]
	v_lshl_add_u64 v[108:109], v[100:101], 0, v[138:139]
	s_waitcnt vmcnt(15)
	v_lshlrev_b32_e32 v110, 16, v196
	v_and_b32_e32 v111, 0xffff0000, v196
	v_lshlrev_b32_e32 v100, 16, v197
	v_and_b32_e32 v101, 0xffff0000, v197
	s_waitcnt vmcnt(14)
	v_lshlrev_b32_e32 v114, 16, v200
	v_and_b32_e32 v115, 0xffff0000, v200
	v_lshlrev_b32_e32 v104, 16, v201
	v_and_b32_e32 v105, 0xffff0000, v201
	v_lshlrev_b32_e32 v112, 16, v198
	v_and_b32_e32 v113, 0xffff0000, v198
	v_lshlrev_b32_e32 v102, 16, v199
	v_and_b32_e32 v103, 0xffff0000, v199
	v_lshlrev_b32_e32 v116, 16, v202
	v_and_b32_e32 v117, 0xffff0000, v202
	v_lshlrev_b32_e32 v106, 16, v203
	v_and_b32_e32 v107, 0xffff0000, v203
	v_pk_add_f32 v[96:97], v[96:97], v[100:101]
	v_pk_add_f32 v[94:95], v[94:95], v[110:111]
	v_pk_add_f32 v[88:89], v[88:89], v[104:105]
	v_pk_add_f32 v[86:87], v[86:87], v[114:115]
	v_pk_add_f32 v[92:93], v[92:93], v[102:103]
	v_pk_add_f32 v[90:91], v[90:91], v[112:113]
	v_pk_add_f32 v[100:101], v[84:85], v[106:107]
	v_pk_add_f32 v[102:103], v[82:83], v[116:117]
	v_mul_f32_e32 v84, v95, v95
	v_mul_f32_e32 v85, v97, v97
	v_mul_f32_e32 v104, v87, v87
	v_mul_f32_e32 v105, v89, v89
	v_cvt_pk_bf16_f32 v82, v94, v95
	v_mul_f32_e32 v95, v91, v91
	v_mul_f32_e32 v106, v103, v103
	v_fmac_f32_e32 v84, v94, v94
	v_fmac_f32_e32 v85, v96, v96
	v_fmac_f32_e32 v104, v86, v86
	v_fmac_f32_e32 v105, v88, v88
	v_cvt_pk_bf16_f32 v83, v96, v97
	v_mul_f32_e32 v97, v93, v93
	v_mul_f32_e32 v107, v101, v101
	v_fmac_f32_e32 v95, v90, v90
	v_fmac_f32_e32 v106, v102, v102
	v_add_f32_e32 v84, v84, v85
	v_add_f32_e32 v85, v104, v105
	v_fmac_f32_e32 v97, v92, v92
	v_fmac_f32_e32 v107, v100, v100
	v_add_f32_e32 v84, v95, v84
	v_add_f32_e32 v85, v106, v85
	v_add_f32_e32 v84, v97, v84
	v_add_f32_e32 v85, v107, v85
	v_add_f32_e32 v94, v84, v85
	ds_bpermute_b32 v95, v160, v94
	v_cvt_pk_bf16_f32 v84, v90, v91
	v_cvt_pk_bf16_f32 v85, v92, v93
	global_store_dwordx4 v[108:109], v[82:85], off sc0 sc1
	s_waitcnt lgkmcnt(0)
	s_nop 0
	v_add_f32_e32 v82, v94, v95
	ds_bpermute_b32 v83, v159, v82
	v_cvt_pk_bf16_f32 v84, v86, v87
	v_cvt_pk_bf16_f32 v85, v88, v89
	v_cvt_pk_bf16_f32 v86, v102, v103
	v_cvt_pk_bf16_f32 v87, v100, v101
	global_store_dwordx4 v[108:109], v[84:87], off offset:256 sc0 sc1
	s_and_saveexec_b64 s[24:25], s[2:3]
	s_cbranch_execz .LBB0_1339
	v_lshl_add_u64 v[84:85], v[98:99], 2, s[6:7]
	s_waitcnt lgkmcnt(0)
	v_add_f32_e32 v82, v82, v83
	global_atomic_add_f32 v[84:85], v82, off
.LBB0_1339:
	s_or_b64 exec, exec, s[24:25]
	v_or_b32_e32 v82, 48, v148
	s_waitcnt lgkmcnt(0)
	v_ashrrev_i32_e32 v83, 31, v82
	v_lshlrev_b64 v[84:85], 12, v[82:83]
	v_lshl_add_u64 v[84:85], s[36:37], 0, v[84:85]
	v_lshl_add_u64 v[92:93], v[84:85], 0, v[138:139]
	s_waitcnt vmcnt(15)
	v_lshlrev_b32_e32 v94, 16, v204
	v_and_b32_e32 v95, 0xffff0000, v204
	v_lshlrev_b32_e32 v84, 16, v205
	v_and_b32_e32 v85, 0xffff0000, v205
	s_waitcnt vmcnt(14)
	v_lshlrev_b32_e32 v98, 16, v208
	v_and_b32_e32 v99, 0xffff0000, v208
	v_lshlrev_b32_e32 v88, 16, v209
	v_and_b32_e32 v89, 0xffff0000, v209
	v_lshlrev_b32_e32 v96, 16, v206
	v_and_b32_e32 v97, 0xffff0000, v206
	v_lshlrev_b32_e32 v86, 16, v207
	v_and_b32_e32 v87, 0xffff0000, v207
	v_lshlrev_b32_e32 v100, 16, v210
	v_and_b32_e32 v101, 0xffff0000, v210
	v_lshlrev_b32_e32 v90, 16, v211
	v_and_b32_e32 v91, 0xffff0000, v211
	v_pk_add_f32 v[80:81], v[80:81], v[84:85]
	v_pk_add_f32 v[78:79], v[78:79], v[94:95]
	v_pk_add_f32 v[72:73], v[72:73], v[88:89]
	v_pk_add_f32 v[70:71], v[70:71], v[98:99]
	v_pk_add_f32 v[76:77], v[76:77], v[86:87]
	v_pk_add_f32 v[74:75], v[74:75], v[96:97]
	v_pk_add_f32 v[84:85], v[68:69], v[90:91]
	v_pk_add_f32 v[86:87], v[66:67], v[100:101]
	v_mul_f32_e32 v68, v79, v79
	v_mul_f32_e32 v69, v81, v81
	v_mul_f32_e32 v88, v71, v71
	v_mul_f32_e32 v89, v73, v73
	v_cvt_pk_bf16_f32 v66, v78, v79
	v_mul_f32_e32 v79, v75, v75
	v_mul_f32_e32 v90, v87, v87
	v_fmac_f32_e32 v68, v78, v78
	v_fmac_f32_e32 v69, v80, v80
	v_fmac_f32_e32 v88, v70, v70
	v_fmac_f32_e32 v89, v72, v72
	v_cvt_pk_bf16_f32 v67, v80, v81
	v_mul_f32_e32 v81, v77, v77
	v_mul_f32_e32 v91, v85, v85
	v_fmac_f32_e32 v79, v74, v74
	v_fmac_f32_e32 v90, v86, v86
	v_add_f32_e32 v68, v68, v69
	v_add_f32_e32 v69, v88, v89
	v_fmac_f32_e32 v81, v76, v76
	v_fmac_f32_e32 v91, v84, v84
	v_add_f32_e32 v68, v79, v68
	v_add_f32_e32 v69, v90, v69
	v_add_f32_e32 v68, v81, v68
	v_add_f32_e32 v69, v91, v69
	v_add_f32_e32 v78, v68, v69
	ds_bpermute_b32 v79, v160, v78
	v_cvt_pk_bf16_f32 v68, v74, v75
	v_cvt_pk_bf16_f32 v69, v76, v77
	global_store_dwordx4 v[92:93], v[66:69], off sc0 sc1
	s_waitcnt lgkmcnt(0)
	s_nop 0
	v_add_f32_e32 v66, v78, v79
	ds_bpermute_b32 v67, v159, v66
	v_cvt_pk_bf16_f32 v68, v70, v71
	v_cvt_pk_bf16_f32 v69, v72, v73
	v_cvt_pk_bf16_f32 v70, v86, v87
	v_cvt_pk_bf16_f32 v71, v84, v85
	global_store_dwordx4 v[92:93], v[68:71], off offset:256 sc0 sc1
	s_and_saveexec_b64 s[24:25], s[2:3]
	s_cbranch_execz .LBB0_1341
	v_lshl_add_u64 v[68:69], v[82:83], 2, s[6:7]
	s_waitcnt lgkmcnt(0)
	v_add_f32_e32 v66, v66, v67
	global_atomic_add_f32 v[68:69], v66, off

; #define LAS __attribute__((address_space(3)))
; __device__ __forceinline__ unsigned cvtpk(float lo, float hi) { f32x2_t v = {lo, hi}; bf16x2_t b = __builtin_convertvector(v, bf16x2_t); return __builtin_bit_cast(unsigned, b); }
;     __device__ __forceinline__ void operator()(const f32x4 (&acc)[2][2][4][2], const Unit& u, int wr, int wc, int fr, int fq) const {
;     ...
;                 const int row = row0 + ai * 128 + m * 16;
;                 const float rs = ((const LAS float*)131072)[wr * 64 + fr + ai * 128 + m * 16] * cs;
; #pragma unroll
;                 for (int bj = 0; bj < 2; ++bj) {
;                     const f32x4 v0 = acc[ai][bj][m][0] * rs, v1 = acc[ai][bj][m][1] * rs;
;                     u32x4 w; w.x = cvtpk(v0[0], v0[1]); w.y = cvtpk(v0[2], v0[3]); w.z = cvtpk(v1[0], v1[1]); w.w = cvtpk(v1[2], v1[3]);
;                     st16(O + (size_t)row * D + col0 + bj * 128, w);
;                 }
.LBB0_1440:
	ds_read2_b32 v[156:157], v148 offset1:16
	v_lshl_add_u32 v158, s16, 8, v146
	v_lshl_or_b32 v160, s44, 8, v149
	v_ashrrev_i32_e32 v159, 31, v158
	v_ashrrev_i32_e32 v161, 31, v160
	s_waitcnt lgkmcnt(0)
	v_mul_f32_e32 v156, 0x3d8293ee, v156
	v_lshlrev_b64 v[162:163], 12, v[158:159]
	v_pk_mul_f32 v[128:129], v[128:129], v[156:157] op_sel_hi:[1,0]
	v_pk_mul_f32 v[126:127], v[126:127], v[156:157] op_sel_hi:[1,0]
	v_pk_mul_f32 v[122:123], v[122:123], v[156:157] op_sel_hi:[1,0]
	v_pk_mul_f32 v[164:165], v[124:125], v[156:157] op_sel_hi:[1,0]
	v_cvt_pk_bf16_f32 v124, v126, v127
	v_cvt_pk_bf16_f32 v125, v128, v129
	v_cvt_pk_bf16_f32 v126, v122, v123
	v_lshl_add_u64 v[122:123], s[94:95], 0, v[162:163]
	v_lshlrev_b64 v[128:129], 1, v[160:161]
	v_cvt_pk_bf16_f32 v127, v164, v165
	v_lshl_add_u64 v[122:123], v[122:123], 0, v[128:129]
	global_store_dwordx4 v[122:123], v[124:127], off sc0 sc1
	v_pk_mul_f32 v[116:117], v[116:117], v[156:157] op_sel_hi:[1,0]
	v_pk_mul_f32 v[114:115], v[114:115], v[156:157] op_sel_hi:[1,0]
	v_pk_mul_f32 v[124:125], v[108:109], v[156:157] op_sel_hi:[1,0]
	v_pk_mul_f32 v[108:109], v[106:107], v[156:157] op_sel_hi:[1,0]
	v_cvt_pk_bf16_f32 v106, v114, v115
	v_cvt_pk_bf16_f32 v107, v116, v117
	v_cvt_pk_bf16_f32 v108, v108, v109
	v_cvt_pk_bf16_f32 v109, v124, v125
	global_store_dwordx4 v[122:123], v[106:109], off offset:256 sc0 sc1
	v_mul_f32_e32 v114, 0x3d8293ee, v157
	v_pk_mul_f32 v[110:111], v[110:111], v[114:115] op_sel_hi:[1,0]
	v_or_b32_e32 v106, 16, v158
	v_ashrrev_i32_e32 v107, 31, v106
	v_lshlrev_b64 v[116:117], 12, v[106:107]
	v_pk_mul_f32 v[108:109], v[120:121], v[114:115] op_sel_hi:[1,0]
	v_pk_mul_f32 v[106:107], v[118:119], v[114:115] op_sel_hi:[1,0]
	v_pk_mul_f32 v[112:113], v[112:113], v[114:115] op_sel_hi:[1,0]
	v_cvt_pk_bf16_f32 v106, v106, v107
	v_cvt_pk_bf16_f32 v107, v108, v109
	v_cvt_pk_bf16_f32 v108, v110, v111
	v_lshl_add_u64 v[110:111], s[94:95], 0, v[116:117]
	v_cvt_pk_bf16_f32 v109, v112, v113
	v_lshl_add_u64 v[110:111], v[110:111], 0, v[128:129]
	v_pk_mul_f32 v[102:103], v[102:103], v[114:115] op_sel_hi:[1,0]
	global_store_dwordx4 v[110:111], v[106:109], off sc0 sc1
	v_pk_mul_f32 v[104:105], v[104:105], v[114:115] op_sel_hi:[1,0]
	s_mov_b32 s13, 0x80000
	v_pk_mul_f32 v[106:107], v[96:97], v[114:115] op_sel_hi:[1,0]
	v_pk_mul_f32 v[96:97], v[94:95], v[114:115] op_sel_hi:[1,0]
	v_cvt_pk_bf16_f32 v94, v102, v103
	ds_read2_b32 v[102:103], v148 offset0:32 offset1:48
	v_cvt_pk_bf16_f32 v95, v104, v105
	v_cvt_pk_bf16_f32 v96, v96, v97
	v_cvt_pk_bf16_f32 v97, v106, v107
	global_store_dwordx4 v[110:111], v[94:97], off offset:256 sc0 sc1
	s_mov_b64 s[22:23], 0x80000
	s_nop 0
	v_or_b32_e32 v94, 32, v158
	v_ashrrev_i32_e32 v95, 31, v94
	s_waitcnt lgkmcnt(0)
	v_mul_f32_e32 v96, 0x3d8293ee, v102
	v_lshlrev_b64 v[94:95], 12, v[94:95]
	v_pk_mul_f32 v[100:101], v[100:101], v[96:97] op_sel_hi:[1,0]
	v_pk_mul_f32 v[98:99], v[98:99], v[96:97] op_sel_hi:[1,0]
	v_pk_mul_f32 v[104:105], v[92:93], v[96:97] op_sel_hi:[1,0]
	v_pk_mul_f32 v[92:93], v[90:91], v[96:97] op_sel_hi:[1,0]
	v_lshl_add_u64 v[94:95], s[94:95], 0, v[94:95]
	v_cvt_pk_bf16_f32 v90, v98, v99
	v_cvt_pk_bf16_f32 v91, v100, v101
	v_cvt_pk_bf16_f32 v92, v92, v93
	v_cvt_pk_bf16_f32 v93, v104, v105
	v_lshl_add_u64 v[94:95], v[94:95], 0, v[128:129]
	global_store_dwordx4 v[94:95], v[90:93], off sc0 sc1
	v_pk_mul_f32 v[84:85], v[84:85], v[96:97] op_sel_hi:[1,0]
	v_pk_mul_f32 v[82:83], v[82:83], v[96:97] op_sel_hi:[1,0]
	v_pk_mul_f32 v[90:91], v[76:77], v[96:97] op_sel_hi:[1,0]
	v_pk_mul_f32 v[76:77], v[74:75], v[96:97] op_sel_hi:[1,0]
	v_cvt_pk_bf16_f32 v74, v82, v83
	v_cvt_pk_bf16_f32 v75, v84, v85
	v_cvt_pk_bf16_f32 v76, v76, v77
	v_cvt_pk_bf16_f32 v77, v90, v91
	global_store_dwordx4 v[94:95], v[74:77], off offset:256 sc0 sc1
	v_mul_f32_e32 v82, 0x3d8293ee, v103
	v_pk_mul_f32 v[78:79], v[78:79], v[82:83] op_sel_hi:[1,0]
	v_or_b32_e32 v74, 48, v158
	v_ashrrev_i32_e32 v75, 31, v74
	v_lshlrev_b64 v[84:85], 12, v[74:75]
	v_pk_mul_f32 v[76:77], v[88:89], v[82:83] op_sel_hi:[1,0]
	v_pk_mul_f32 v[74:75], v[86:87], v[82:83] op_sel_hi:[1,0]
	v_pk_mul_f32 v[80:81], v[80:81], v[82:83] op_sel_hi:[1,0]
	v_cvt_pk_bf16_f32 v74, v74, v75
	v_cvt_pk_bf16_f32 v75, v76, v77
	v_cvt_pk_bf16_f32 v76, v78, v79
	v_lshl_add_u64 v[78:79], s[94:95], 0, v[84:85]
	v_cvt_pk_bf16_f32 v77, v80, v81
	v_lshl_add_u64 v[78:79], v[78:79], 0, v[128:129]
	v_pk_mul_f32 v[70:71], v[70:71], v[82:83] op_sel_hi:[1,0]
	global_store_dwordx4 v[78:79], v[74:77], off sc0 sc1
	v_pk_mul_f32 v[72:73], v[72:73], v[82:83] op_sel_hi:[1,0]
	s_nop 0
	v_pk_mul_f32 v[74:75], v[68:69], v[82:83] op_sel_hi:[1,0]
	v_pk_mul_f32 v[68:69], v[66:67], v[82:83] op_sel_hi:[1,0]
	v_cvt_pk_bf16_f32 v66, v70, v71
	ds_read2_b32 v[70:71], v148 offset0:128 offset1:144
	v_cvt_pk_bf16_f32 v67, v72, v73
	v_cvt_pk_bf16_f32 v68, v68, v69
	v_cvt_pk_bf16_f32 v69, v74, v75
	global_store_dwordx4 v[78:79], v[66:69], off offset:256 sc0 sc1
	s_waitcnt lgkmcnt(0)
; #define LAS __attribute__((address_space(3)))
; __device__ __forceinline__ unsigned cvtpk(float lo, float hi) { f32x2_t v = {lo, hi}; bf16x2_t b = __builtin_convertvector(v, bf16x2_t); return __builtin_bit_cast(unsigned, b); }
;     __device__ __forceinline__ void operator()(const f32x4 (&acc)[2][2][4][2], const Unit& u, int wr, int wc, int fr, int fq) const {
;     ...
;         for (int ai = 0; ai < 2; ++ai)
; #pragma unroll
;             for (int m = 0; m < 4; ++m) {
;                 const int row = row0 + ai * 128 + m * 16;
;                 const float rs = ((const LAS float*)131072)[wr * 64 + fr + ai * 128 + m * 16] * cs;
; #pragma unroll
;                 for (int bj = 0; bj < 2; ++bj) {
;                     const f32x4 v0 = acc[ai][bj][m][0] * rs, v1 = acc[ai][bj][m][1] * rs;
;                     u32x4 w; w.x = cvtpk(v0[0], v0[1]); w.y = cvtpk(v0[2], v0[3]); w.z = cvtpk(v1[0], v1[1]); w.w = cvtpk(v1[2], v1[3]);
;                     st16(O + (size_t)row * D + col0 + bj * 128, w);
;                 }
	s_nop 0
	v_mul_f32_e32 v66, 0x3d8293ee, v70
	v_pk_mul_f32 v[64:65], v[64:65], v[66:67] op_sel_hi:[1,0]
	v_pk_mul_f32 v[62:63], v[62:63], v[66:67] op_sel_hi:[1,0]
	v_pk_mul_f32 v[68:69], v[60:61], v[66:67] op_sel_hi:[1,0]
	v_pk_mul_f32 v[60:61], v[58:59], v[66:67] op_sel_hi:[1,0]
	v_cvt_pk_bf16_f32 v59, v64, v65
	v_add_co_u32_e32 v64, vcc, s13, v122
	v_cvt_pk_bf16_f32 v58, v62, v63
	v_cvt_pk_bf16_f32 v60, v60, v61
	v_cvt_pk_bf16_f32 v61, v68, v69
	v_addc_co_u32_e32 v65, vcc, 0, v123, vcc
	global_store_dwordx4 v[64:65], v[58:61], off
	v_pk_mul_f32 v[52:53], v[52:53], v[66:67] op_sel_hi:[1,0]
	v_pk_mul_f32 v[50:51], v[50:51], v[66:67] op_sel_hi:[1,0]
	v_pk_mul_f32 v[58:59], v[44:45], v[66:67] op_sel_hi:[1,0]
	v_pk_mul_f32 v[44:45], v[42:43], v[66:67] op_sel_hi:[1,0]
	v_lshl_add_u64 v[62:63], v[122:123], 0, s[22:23]
	v_cvt_pk_bf16_f32 v42, v50, v51
	v_cvt_pk_bf16_f32 v43, v52, v53
	v_cvt_pk_bf16_f32 v44, v44, v45
	v_cvt_pk_bf16_f32 v45, v58, v59
	v_mul_f32_e32 v50, 0x3d8293ee, v71
	global_store_dwordx4 v[62:63], v[42:45], off offset:256
	v_pk_mul_f32 v[48:49], v[48:49], v[50:51] op_sel_hi:[1,0]
	s_mov_b32 s13, 0x90000
	v_pk_mul_f32 v[44:45], v[56:57], v[50:51] op_sel_hi:[1,0]
	v_pk_mul_f32 v[42:43], v[54:55], v[50:51] op_sel_hi:[1,0]
	v_pk_mul_f32 v[46:47], v[46:47], v[50:51] op_sel_hi:[1,0]
	v_cvt_pk_bf16_f32 v42, v42, v43
	v_cvt_pk_bf16_f32 v43, v44, v45
	v_cvt_pk_bf16_f32 v45, v48, v49
	v_add_co_u32_e32 v48, vcc, s13, v122
	v_cvt_pk_bf16_f32 v44, v46, v47
	s_nop 0
	v_addc_co_u32_e32 v49, vcc, 0, v123, vcc
	v_pk_mul_f32 v[34:35], v[34:35], v[50:51] op_sel_hi:[1,0]
	global_store_dwordx4 v[48:49], v[42:45], off
	s_mov_b64 s[22:23], 0x90000
	v_pk_mul_f32 v[36:37], v[36:37], v[50:51] op_sel_hi:[1,0]
	v_pk_mul_f32 v[42:43], v[28:29], v[50:51] op_sel_hi:[1,0]
	v_pk_mul_f32 v[28:29], v[26:27], v[50:51] op_sel_hi:[1,0]
	v_cvt_pk_bf16_f32 v26, v34, v35
	ds_read2_b32 v[34:35], v148 offset0:160 offset1:176
	v_lshl_add_u64 v[46:47], v[122:123], 0, s[22:23]
	v_cvt_pk_bf16_f32 v27, v36, v37
	v_cvt_pk_bf16_f32 v28, v28, v29
	v_cvt_pk_bf16_f32 v29, v42, v43
	s_waitcnt lgkmcnt(0)
	v_mul_f32_e32 v34, 0x3d8293ee, v34
	global_store_dwordx4 v[46:47], v[26:29], off offset:256
	v_pk_mul_f32 v[32:33], v[32:33], v[34:35] op_sel_hi:[1,0]
	s_mov_b32 s13, 0xa0000
	v_pk_mul_f32 v[28:29], v[40:41], v[34:35] op_sel_hi:[1,0]
	v_pk_mul_f32 v[26:27], v[38:39], v[34:35] op_sel_hi:[1,0]
	v_pk_mul_f32 v[30:31], v[30:31], v[34:35] op_sel_hi:[1,0]
	v_cvt_pk_bf16_f32 v26, v26, v27
	v_cvt_pk_bf16_f32 v27, v28, v29
	v_cvt_pk_bf16_f32 v29, v32, v33
	v_add_co_u32_e32 v32, vcc, s13, v122
	v_cvt_pk_bf16_f32 v28, v30, v31
	s_nop 0
	v_addc_co_u32_e32 v33, vcc, 0, v123, vcc
	s_mov_b64 s[22:23], 0xa0000
	global_store_dwordx4 v[32:33], v[26:29], off
	v_pk_mul_f32 v[20:21], v[20:21], v[34:35] op_sel_hi:[1,0]
	v_pk_mul_f32 v[18:19], v[18:19], v[34:35] op_sel_hi:[1,0]
	v_pk_mul_f32 v[26:27], v[12:13], v[34:35] op_sel_hi:[1,0]
	v_pk_mul_f32 v[12:13], v[10:11], v[34:35] op_sel_hi:[1,0]
	v_lshl_add_u64 v[30:31], v[122:123], 0, s[22:23]
	v_cvt_pk_bf16_f32 v10, v18, v19
	v_cvt_pk_bf16_f32 v11, v20, v21
	v_cvt_pk_bf16_f32 v12, v12, v13
	v_cvt_pk_bf16_f32 v13, v26, v27
	v_mul_f32_e32 v18, 0x3d8293ee, v35
	global_store_dwordx4 v[30:31], v[10:13], off offset:256
	v_pk_mul_f32 v[16:17], v[16:17], v[18:19] op_sel_hi:[1,0]
	s_mov_b32 s13, 0xb0000
	v_pk_mul_f32 v[12:13], v[24:25], v[18:19] op_sel_hi:[1,0]
	v_pk_mul_f32 v[10:11], v[22:23], v[18:19] op_sel_hi:[1,0]
	v_pk_mul_f32 v[14:15], v[14:15], v[18:19] op_sel_hi:[1,0]
	v_cvt_pk_bf16_f32 v10, v10, v11
	v_cvt_pk_bf16_f32 v11, v12, v13
	v_cvt_pk_bf16_f32 v13, v16, v17
	v_add_co_u32_e32 v16, vcc, s13, v122
	v_cvt_pk_bf16_f32 v12, v14, v15
	s_nop 0
	v_addc_co_u32_e32 v17, vcc, 0, v123, vcc
	s_mov_b64 s[22:23], 0xb0000
	global_store_dwordx4 v[16:17], v[10:13], off
	v_pk_mul_f32 v[8:9], v[8:9], v[18:19] op_sel_hi:[1,0]
	v_pk_mul_f32 v[6:7], v[6:7], v[18:19] op_sel_hi:[1,0]
	v_pk_mul_f32 v[10:11], v[4:5], v[18:19] op_sel_hi:[1,0]
	v_pk_mul_f32 v[4:5], v[2:3], v[18:19] op_sel_hi:[1,0]
	v_lshl_add_u64 v[14:15], v[122:123], 0, s[22:23]
	v_cvt_pk_bf16_f32 v2, v6, v7
	v_cvt_pk_bf16_f32 v3, v8, v9
	v_cvt_pk_bf16_f32 v4, v4, v5
	v_cvt_pk_bf16_f32 v5, v10, v11
	s_andn2_b64 vcc, exec, s[2:3]
	s_mov_b64 s[2:3], -1
	global_store_dwordx4 v[14:15], v[2:5], off offset:256
	s_cbranch_vccnz .LBB0_1429
	s_andn2_b64 vcc, exec, s[6:7]
	s_cbranch_vccnz .LBB0_1428
	s_barrier
	s_branch .LBB0_1428

; __device__ __forceinline__ unsigned cvtpk(float lo, float hi) { f32x2_t v = {lo, hi}; bf16x2_t b = __builtin_convertvector(v, bf16x2_t); return __builtin_bit_cast(unsigned, b); }
; __device__ __forceinline__ float bflo(unsigned w) { return __uint_as_float(w << 16); }
; __device__ __forceinline__ float bfhi(unsigned w) { return __uint_as_float(w & 0xffff0000u); }
;     __device__ __forceinline__ void operator()(const f32x4 (&acc)[2][2][4][2], const Unit& u, int wr, int wc, int fr, int fq) const {
;     ...
;                 const int row = row0 + ai * 128 + m * 16; float s = 0.f;
; #pragma unroll
;                 for (int bj = 0; bj < 2; ++bj) {
;                     const size_t off = (size_t)row * D + col0 + bj * 128;
;                     f32x4 b0, b1;
;                     if (BASE_F32) { b0 = __builtin_nontemporal_load((const f32x4*)(base + off)); b1 = __builtin_nontemporal_load((const f32x4*)(base + off + 4)); }
;                     else { const u32x4 w = *(const u32x4*)(xb + off); b0 = (f32x4){bflo(w.x), bfhi(w.x), bflo(w.y), bfhi(w.y)}; b1 = (f32x4){bflo(w.z), bfhi(w.z), bflo(w.w), bfhi(w.w)}; }
;                     const f32x4 h0 = b0 + acc[ai][bj][m][0] * scale, h1 = b1 + acc[ai][bj][m][1] * scale;
;                     if (OUT_F32) { *(f32x4*)(out + off) = h0; *(f32x4*)(out + off + 4) = h1; }
;                     else { u32x4 w; w.x = cvtpk(h0[0], h0[1]); w.y = cvtpk(h0[2], h0[3]); w.z = cvtpk(h1[0], h1[1]); w.w = cvtpk(h1[2], h1[3]); st16(xb + off, w); }
;                     s += (h0[0] * h0[0] + h0[1] * h0[1]) + (h0[2] * h0[2] + h0[3] * h0[3]) + (h1[0] * h1[0] + h1[1] * h1[1]) + (h1[2] * h1[2] + h1[3] * h1[3]);
;                 }
;                 s += __shfl_xor(s, 16); s += __shfl_xor(s, 32);
;                 if (fq == 0) __hip_atomic_fetch_add(ssq_out + row, s, __ATOMIC_RELAXED, __HIP_MEMORY_SCOPE_AGENT);
.LBB0_1607:
	v_lshl_add_u32 v148, s24, 8, v150
	s_lshl_b32 s17, s26, 8
	s_and_b32 s17, s17, 0x700
	v_ashrrev_i32_e32 v149, 31, v148
	v_or_b32_e32 v138, s17, v152
	v_lshlrev_b64 v[158:159], 12, v[148:149]
	v_lshl_add_u64 v[158:159], s[36:37], 0, v[158:159]
	v_lshlrev_b32_e32 v138, 1, v138
	v_lshl_add_u64 v[168:169], v[158:159], 0, v[138:139]
	global_load_dwordx4 v[160:163], v[168:169], off
	global_load_dwordx4 v[164:167], v[168:169], off offset:256
	v_or_b32_e32 v178, 16, v148
	v_ashrrev_i32_e32 v179, 31, v178
	v_lshlrev_b64 v[178:179], 12, v[178:179]
	v_lshl_add_u64 v[178:179], s[36:37], 0, v[178:179]
	v_lshl_add_u64 v[178:179], v[178:179], 0, v[138:139]
	global_load_dwordx4 v[180:183], v[178:179], off
	global_load_dwordx4 v[184:187], v[178:179], off offset:256
	v_or_b32_e32 v178, 32, v148
	v_ashrrev_i32_e32 v179, 31, v178
	v_lshlrev_b64 v[178:179], 12, v[178:179]
	v_lshl_add_u64 v[178:179], s[36:37], 0, v[178:179]
	v_lshl_add_u64 v[178:179], v[178:179], 0, v[138:139]
	global_load_dwordx4 v[192:195], v[178:179], off
	global_load_dwordx4 v[196:199], v[178:179], off offset:256
	v_or_b32_e32 v178, 48, v148
	v_ashrrev_i32_e32 v179, 31, v178
	v_lshlrev_b64 v[178:179], 12, v[178:179]
	v_lshl_add_u64 v[178:179], s[36:37], 0, v[178:179]
	v_lshl_add_u64 v[178:179], v[178:179], 0, v[138:139]
	global_load_dwordx4 v[200:203], v[178:179], off
	global_load_dwordx4 v[204:207], v[178:179], off offset:256
	v_add_u32_e32 v178, 0x80, v148
	v_ashrrev_i32_e32 v179, 31, v178
	v_lshlrev_b64 v[178:179], 12, v[178:179]
	v_lshl_add_u64 v[178:179], s[36:37], 0, v[178:179]
	v_lshl_add_u64 v[178:179], v[178:179], 0, v[138:139]
	global_load_dwordx4 v[208:211], v[178:179], off
	global_load_dwordx4 v[212:215], v[178:179], off offset:256
	v_add_u32_e32 v178, 0x90, v148
	v_ashrrev_i32_e32 v179, 31, v178
	v_lshlrev_b64 v[178:179], 12, v[178:179]
	v_lshl_add_u64 v[178:179], s[36:37], 0, v[178:179]
	v_lshl_add_u64 v[178:179], v[178:179], 0, v[138:139]
	global_load_dwordx4 v[216:219], v[178:179], off
	global_load_dwordx4 v[220:223], v[178:179], off offset:256
	v_add_u32_e32 v178, 0xa0, v148
	v_ashrrev_i32_e32 v179, 31, v178
	v_lshlrev_b64 v[178:179], 12, v[178:179]
	v_lshl_add_u64 v[178:179], s[36:37], 0, v[178:179]
	v_lshl_add_u64 v[178:179], v[178:179], 0, v[138:139]
	global_load_dwordx4 v[224:227], v[178:179], off
	global_load_dwordx4 v[228:231], v[178:179], off offset:256
	v_and_b32_e32 v158, 64, v156
	v_xor_b32_e32 v157, 16, v156
	v_add_u32_e32 v158, 64, v158
	v_xor_b32_e32 v159, 32, v156
	v_cmp_lt_i32_e32 vcc, v157, v158
	s_waitcnt vmcnt(12)
	v_lshlrev_b32_e32 v170, 16, v160
	v_cndmask_b32_e32 v157, v156, v157, vcc
	v_cmp_lt_i32_e32 vcc, v159, v158
	v_and_b32_e32 v171, 0xffff0000, v160
	v_lshlrev_b32_e32 v160, 16, v161
	v_and_b32_e32 v161, 0xffff0000, v161
	v_lshlrev_b32_e32 v174, 16, v164
	v_and_b32_e32 v175, 0xffff0000, v164
	v_lshlrev_b32_e32 v164, 16, v165
	v_and_b32_e32 v165, 0xffff0000, v165
	v_cndmask_b32_e32 v159, v156, v159, vcc
	v_lshlrev_b32_e32 v172, 16, v162
	v_and_b32_e32 v173, 0xffff0000, v162
	v_lshlrev_b32_e32 v162, 16, v163
	v_and_b32_e32 v163, 0xffff0000, v163
	v_lshlrev_b32_e32 v176, 16, v166
	v_and_b32_e32 v177, 0xffff0000, v166
	v_lshlrev_b32_e32 v166, 16, v167
	v_and_b32_e32 v167, 0xffff0000, v167
	v_pk_add_f32 v[128:129], v[128:129], v[160:161]
	v_pk_add_f32 v[126:127], v[126:127], v[170:171]
	v_pk_add_f32 v[120:121], v[120:121], v[164:165]
	v_pk_add_f32 v[118:119], v[118:119], v[174:175]
	v_lshlrev_b32_e32 v158, 2, v157
	v_lshlrev_b32_e32 v157, 2, v159
	v_pk_add_f32 v[124:125], v[124:125], v[162:163]
	v_pk_add_f32 v[122:123], v[122:123], v[172:173]
	v_pk_add_f32 v[160:161], v[116:117], v[166:167]
	v_pk_add_f32 v[162:163], v[114:115], v[176:177]
	v_mul_f32_e32 v116, v127, v127
	v_mul_f32_e32 v117, v129, v129
	v_mul_f32_e32 v159, v119, v119
	v_mul_f32_e32 v164, v121, v121
	v_cvt_pk_bf16_f32 v114, v126, v127
	v_mul_f32_e32 v127, v123, v123
	v_mul_f32_e32 v165, v163, v163
	v_fmac_f32_e32 v116, v126, v126
	v_fmac_f32_e32 v117, v128, v128
	v_fmac_f32_e32 v159, v118, v118
	v_fmac_f32_e32 v164, v120, v120
	v_cvt_pk_bf16_f32 v115, v128, v129
	v_mul_f32_e32 v129, v125, v125
	v_mul_f32_e32 v166, v161, v161
	v_fmac_f32_e32 v127, v122, v122
	v_fmac_f32_e32 v165, v162, v162
	v_add_f32_e32 v116, v116, v117
	v_add_f32_e32 v117, v159, v164
	v_fmac_f32_e32 v129, v124, v124
	v_fmac_f32_e32 v166, v160, v160
	v_add_f32_e32 v116, v127, v116
	v_add_f32_e32 v117, v165, v117
	v_add_f32_e32 v116, v129, v116
	v_add_f32_e32 v117, v166, v117
	v_add_f32_e32 v126, v116, v117
	ds_bpermute_b32 v127, v158, v126
	v_cvt_pk_bf16_f32 v116, v122, v123
	v_cvt_pk_bf16_f32 v117, v124, v125
	global_store_dwordx4 v[168:169], v[114:117], off sc0 sc1
	s_waitcnt lgkmcnt(0)
	s_nop 0
	v_add_f32_e32 v114, v126, v127
	ds_bpermute_b32 v115, v157, v114
	v_cvt_pk_bf16_f32 v116, v118, v119
	v_cvt_pk_bf16_f32 v117, v120, v121
	v_cvt_pk_bf16_f32 v118, v162, v163
	v_cvt_pk_bf16_f32 v119, v160, v161
	global_store_dwordx4 v[168:169], v[116:119], off offset:256 sc0 sc1
	s_and_saveexec_b64 s[24:25], s[2:3]
	s_cbranch_execz .LBB0_1609
	v_lshl_add_u64 v[116:117], v[148:149], 2, s[6:7]
	s_waitcnt lgkmcnt(0)
	v_add_f32_e32 v114, v114, v115
	global_atomic_add_f32 v[116:117], v114, off
; __device__ __forceinline__ unsigned cvtpk(float lo, float hi) { f32x2_t v = {lo, hi}; bf16x2_t b = __builtin_convertvector(v, bf16x2_t); return __builtin_bit_cast(unsigned, b); }
; __device__ __forceinline__ float bflo(unsigned w) { return __uint_as_float(w << 16); }
; __device__ __forceinline__ float bfhi(unsigned w) { return __uint_as_float(w & 0xffff0000u); }
;     __device__ __forceinline__ void operator()(const f32x4 (&acc)[2][2][4][2], const Unit& u, int wr, int wc, int fr, int fq) const {
;     ...
;                 const int row = row0 + ai * 128 + m * 16; float s = 0.f;
; #pragma unroll
;                 for (int bj = 0; bj < 2; ++bj) {
;                     const size_t off = (size_t)row * D + col0 + bj * 128;
;                     f32x4 b0, b1;
;                     if (BASE_F32) { b0 = __builtin_nontemporal_load((const f32x4*)(base + off)); b1 = __builtin_nontemporal_load((const f32x4*)(base + off + 4)); }
;                     else { const u32x4 w = *(const u32x4*)(xb + off); b0 = (f32x4){bflo(w.x), bfhi(w.x), bflo(w.y), bfhi(w.y)}; b1 = (f32x4){bflo(w.z), bfhi(w.z), bflo(w.w), bfhi(w.w)}; }
;                     const f32x4 h0 = b0 + acc[ai][bj][m][0] * scale, h1 = b1 + acc[ai][bj][m][1] * scale;
;                     if (OUT_F32) { *(f32x4*)(out + off) = h0; *(f32x4*)(out + off + 4) = h1; }
;                     else { u32x4 w; w.x = cvtpk(h0[0], h0[1]); w.y = cvtpk(h0[2], h0[3]); w.z = cvtpk(h1[0], h1[1]); w.w = cvtpk(h1[2], h1[3]); st16(xb + off, w); }
;                     s += (h0[0] * h0[0] + h0[1] * h0[1]) + (h0[2] * h0[2] + h0[3] * h0[3]) + (h1[0] * h1[0] + h1[1] * h1[1]) + (h1[2] * h1[2] + h1[3] * h1[3]);
;                 }
;                 s += __shfl_xor(s, 16); s += __shfl_xor(s, 32);
;                 if (fq == 0) __hip_atomic_fetch_add(ssq_out + row, s, __ATOMIC_RELAXED, __HIP_MEMORY_SCOPE_AGENT);
.LBB0_1609:
	s_or_b64 exec, exec, s[24:25]
	v_or_b32_e32 v114, 16, v148
	s_waitcnt lgkmcnt(0)
	v_ashrrev_i32_e32 v115, 31, v114
	v_lshlrev_b64 v[116:117], 12, v[114:115]
	v_lshl_add_u64 v[116:117], s[36:37], 0, v[116:117]
	v_lshl_add_u64 v[124:125], v[116:117], 0, v[138:139]
	s_waitcnt vmcnt(13)
	v_lshlrev_b32_e32 v126, 16, v180
	v_and_b32_e32 v127, 0xffff0000, v180
	v_lshlrev_b32_e32 v116, 16, v181
	v_and_b32_e32 v117, 0xffff0000, v181
	s_waitcnt vmcnt(12)
	v_lshlrev_b32_e32 v160, 16, v184
	v_and_b32_e32 v161, 0xffff0000, v184
	v_lshlrev_b32_e32 v120, 16, v185
	v_and_b32_e32 v121, 0xffff0000, v185
	v_lshlrev_b32_e32 v128, 16, v182
	v_and_b32_e32 v129, 0xffff0000, v182
	v_lshlrev_b32_e32 v118, 16, v183
	v_and_b32_e32 v119, 0xffff0000, v183
	v_lshlrev_b32_e32 v162, 16, v186
	v_and_b32_e32 v163, 0xffff0000, v186
	v_lshlrev_b32_e32 v122, 16, v187
	v_and_b32_e32 v123, 0xffff0000, v187
	v_add_u32_e32 v178, 0xb0, v148
	v_ashrrev_i32_e32 v179, 31, v178
	v_lshlrev_b64 v[178:179], 12, v[178:179]
	v_lshl_add_u64 v[178:179], s[36:37], 0, v[178:179]
	v_lshl_add_u64 v[178:179], v[178:179], 0, v[138:139]
	global_load_dwordx4 v[180:183], v[178:179], off
	global_load_dwordx4 v[184:187], v[178:179], off offset:256
	v_pk_add_f32 v[112:113], v[112:113], v[116:117]
	v_pk_add_f32 v[110:111], v[110:111], v[126:127]
	v_pk_add_f32 v[104:105], v[104:105], v[120:121]
	v_pk_add_f32 v[102:103], v[102:103], v[160:161]
	v_pk_add_f32 v[108:109], v[108:109], v[118:119]
	v_pk_add_f32 v[106:107], v[106:107], v[128:129]
	v_pk_add_f32 v[116:117], v[100:101], v[122:123]
	v_pk_add_f32 v[118:119], v[98:99], v[162:163]
	v_mul_f32_e32 v100, v111, v111
	v_mul_f32_e32 v101, v113, v113
	v_mul_f32_e32 v120, v103, v103
	v_mul_f32_e32 v121, v105, v105
	v_cvt_pk_bf16_f32 v98, v110, v111
	v_mul_f32_e32 v111, v107, v107
	v_mul_f32_e32 v122, v119, v119
	v_fmac_f32_e32 v100, v110, v110
	v_fmac_f32_e32 v101, v112, v112
	v_fmac_f32_e32 v120, v102, v102
	v_fmac_f32_e32 v121, v104, v104
	v_cvt_pk_bf16_f32 v99, v112, v113
	v_mul_f32_e32 v113, v109, v109
	v_mul_f32_e32 v123, v117, v117
	v_fmac_f32_e32 v111, v106, v106
	v_fmac_f32_e32 v122, v118, v118
	v_add_f32_e32 v100, v100, v101
	v_add_f32_e32 v101, v120, v121
	v_fmac_f32_e32 v113, v108, v108
	v_fmac_f32_e32 v123, v116, v116
	v_add_f32_e32 v100, v111, v100
	v_add_f32_e32 v101, v122, v101
	v_add_f32_e32 v100, v113, v100
	v_add_f32_e32 v101, v123, v101
	v_add_f32_e32 v110, v100, v101
	ds_bpermute_b32 v111, v158, v110
	v_cvt_pk_bf16_f32 v100, v106, v107
	v_cvt_pk_bf16_f32 v101, v108, v109
	global_store_dwordx4 v[124:125], v[98:101], off sc0 sc1
	s_waitcnt lgkmcnt(0)
	s_nop 0
	v_add_f32_e32 v98, v110, v111
	ds_bpermute_b32 v99, v157, v98
	v_cvt_pk_bf16_f32 v100, v102, v103
	v_cvt_pk_bf16_f32 v101, v104, v105
	v_cvt_pk_bf16_f32 v102, v118, v119
	v_cvt_pk_bf16_f32 v103, v116, v117
	global_store_dwordx4 v[124:125], v[100:103], off offset:256 sc0 sc1
	s_and_saveexec_b64 s[24:25], s[2:3]
	s_cbranch_execz .LBB0_1611
	v_lshl_add_u64 v[100:101], v[114:115], 2, s[6:7]
	s_waitcnt lgkmcnt(0)
	v_add_f32_e32 v98, v98, v99
	global_atomic_add_f32 v[100:101], v98, off
; __device__ __forceinline__ unsigned cvtpk(float lo, float hi) { f32x2_t v = {lo, hi}; bf16x2_t b = __builtin_convertvector(v, bf16x2_t); return __builtin_bit_cast(unsigned, b); }
; __device__ __forceinline__ float bflo(unsigned w) { return __uint_as_float(w << 16); }
; __device__ __forceinline__ float bfhi(unsigned w) { return __uint_as_float(w & 0xffff0000u); }
;     __device__ __forceinline__ void operator()(const f32x4 (&acc)[2][2][4][2], const Unit& u, int wr, int wc, int fr, int fq) const {
;     ...
;                 const int row = row0 + ai * 128 + m * 16; float s = 0.f;
; #pragma unroll
;                 for (int bj = 0; bj < 2; ++bj) {
;                     const size_t off = (size_t)row * D + col0 + bj * 128;
;                     f32x4 b0, b1;
;                     if (BASE_F32) { b0 = __builtin_nontemporal_load((const f32x4*)(base + off)); b1 = __builtin_nontemporal_load((const f32x4*)(base + off + 4)); }
;                     else { const u32x4 w = *(const u32x4*)(xb + off); b0 = (f32x4){bflo(w.x), bfhi(w.x), bflo(w.y), bfhi(w.y)}; b1 = (f32x4){bflo(w.z), bfhi(w.z), bflo(w.w), bfhi(w.w)}; }
;                     const f32x4 h0 = b0 + acc[ai][bj][m][0] * scale, h1 = b1 + acc[ai][bj][m][1] * scale;
;                     if (OUT_F32) { *(f32x4*)(out + off) = h0; *(f32x4*)(out + off + 4) = h1; }
;                     else { u32x4 w; w.x = cvtpk(h0[0], h0[1]); w.y = cvtpk(h0[2], h0[3]); w.z = cvtpk(h1[0], h1[1]); w.w = cvtpk(h1[2], h1[3]); st16(xb + off, w); }
;                     s += (h0[0] * h0[0] + h0[1] * h0[1]) + (h0[2] * h0[2] + h0[3] * h0[3]) + (h1[0] * h1[0] + h1[1] * h1[1]) + (h1[2] * h1[2] + h1[3] * h1[3]);
;                 }
;                 s += __shfl_xor(s, 16); s += __shfl_xor(s, 32);
;                 if (fq == 0) __hip_atomic_fetch_add(ssq_out + row, s, __ATOMIC_RELAXED, __HIP_MEMORY_SCOPE_AGENT);
.LBB0_1611:
	s_or_b64 exec, exec, s[24:25]
	v_or_b32_e32 v98, 32, v148
	s_waitcnt lgkmcnt(0)
	v_ashrrev_i32_e32 v99, 31, v98
	v_lshlrev_b64 v[100:101], 12, v[98:99]
	v_lshl_add_u64 v[100:101], s[36:37], 0, v[100:101]
	v_lshl_add_u64 v[108:109], v[100:101], 0, v[138:139]
	s_waitcnt vmcnt(15)
	v_lshlrev_b32_e32 v110, 16, v192
	v_and_b32_e32 v111, 0xffff0000, v192
	v_lshlrev_b32_e32 v100, 16, v193
	v_and_b32_e32 v101, 0xffff0000, v193
	s_waitcnt vmcnt(14)
	v_lshlrev_b32_e32 v114, 16, v196
	v_and_b32_e32 v115, 0xffff0000, v196
	v_lshlrev_b32_e32 v104, 16, v197
	v_and_b32_e32 v105, 0xffff0000, v197
	v_lshlrev_b32_e32 v112, 16, v194
	v_and_b32_e32 v113, 0xffff0000, v194
	v_lshlrev_b32_e32 v102, 16, v195
	v_and_b32_e32 v103, 0xffff0000, v195
	v_lshlrev_b32_e32 v116, 16, v198
	v_and_b32_e32 v117, 0xffff0000, v198
	v_lshlrev_b32_e32 v106, 16, v199
	v_and_b32_e32 v107, 0xffff0000, v199
	v_pk_add_f32 v[96:97], v[96:97], v[100:101]
	v_pk_add_f32 v[94:95], v[94:95], v[110:111]
	v_pk_add_f32 v[88:89], v[88:89], v[104:105]
	v_pk_add_f32 v[86:87], v[86:87], v[114:115]
	v_pk_add_f32 v[92:93], v[92:93], v[102:103]
	v_pk_add_f32 v[90:91], v[90:91], v[112:113]
	v_pk_add_f32 v[100:101], v[84:85], v[106:107]
	v_pk_add_f32 v[102:103], v[82:83], v[116:117]
	v_mul_f32_e32 v84, v95, v95
	v_mul_f32_e32 v85, v97, v97
	v_mul_f32_e32 v104, v87, v87
	v_mul_f32_e32 v105, v89, v89
	v_cvt_pk_bf16_f32 v82, v94, v95
	v_mul_f32_e32 v95, v91, v91
	v_mul_f32_e32 v106, v103, v103
	v_fmac_f32_e32 v84, v94, v94
	v_fmac_f32_e32 v85, v96, v96
	v_fmac_f32_e32 v104, v86, v86
	v_fmac_f32_e32 v105, v88, v88
	v_cvt_pk_bf16_f32 v83, v96, v97
	v_mul_f32_e32 v97, v93, v93
	v_mul_f32_e32 v107, v101, v101
	v_fmac_f32_e32 v95, v90, v90
	v_fmac_f32_e32 v106, v102, v102
	v_add_f32_e32 v84, v84, v85
	v_add_f32_e32 v85, v104, v105
	v_fmac_f32_e32 v97, v92, v92
	v_fmac_f32_e32 v107, v100, v100
	v_add_f32_e32 v84, v95, v84
	v_add_f32_e32 v85, v106, v85
	v_add_f32_e32 v84, v97, v84
	v_add_f32_e32 v85, v107, v85
	v_add_f32_e32 v94, v84, v85
	ds_bpermute_b32 v95, v158, v94
	v_cvt_pk_bf16_f32 v84, v90, v91
	v_cvt_pk_bf16_f32 v85, v92, v93
	global_store_dwordx4 v[108:109], v[82:85], off sc0 sc1
	s_waitcnt lgkmcnt(0)
	s_nop 0
	v_add_f32_e32 v82, v94, v95
	ds_bpermute_b32 v83, v157, v82
	v_cvt_pk_bf16_f32 v84, v86, v87
	v_cvt_pk_bf16_f32 v85, v88, v89
	v_cvt_pk_bf16_f32 v86, v102, v103
	v_cvt_pk_bf16_f32 v87, v100, v101
	global_store_dwordx4 v[108:109], v[84:87], off offset:256 sc0 sc1
	s_and_saveexec_b64 s[24:25], s[2:3]
	s_cbranch_execz .LBB0_1613
	v_lshl_add_u64 v[84:85], v[98:99], 2, s[6:7]
	s_waitcnt lgkmcnt(0)
	v_add_f32_e32 v82, v82, v83
	global_atomic_add_f32 v[84:85], v82, off
.LBB0_1613:
	s_or_b64 exec, exec, s[24:25]
	v_or_b32_e32 v82, 48, v148
	s_waitcnt lgkmcnt(0)
	v_ashrrev_i32_e32 v83, 31, v82
	v_lshlrev_b64 v[84:85], 12, v[82:83]
	v_lshl_add_u64 v[84:85], s[36:37], 0, v[84:85]
	v_lshl_add_u64 v[92:93], v[84:85], 0, v[138:139]
	s_waitcnt vmcnt(15)
	v_lshlrev_b32_e32 v94, 16, v200
	v_and_b32_e32 v95, 0xffff0000, v200
	v_lshlrev_b32_e32 v84, 16, v201
	v_and_b32_e32 v85, 0xffff0000, v201
	s_waitcnt vmcnt(14)
	v_lshlrev_b32_e32 v98, 16, v204
	v_and_b32_e32 v99, 0xffff0000, v204
	v_lshlrev_b32_e32 v88, 16, v205
	v_and_b32_e32 v89, 0xffff0000, v205
	v_lshlrev_b32_e32 v96, 16, v202
	v_and_b32_e32 v97, 0xffff0000, v202
	v_lshlrev_b32_e32 v86, 16, v203
	v_and_b32_e32 v87, 0xffff0000, v203
	v_lshlrev_b32_e32 v100, 16, v206
	v_and_b32_e32 v101, 0xffff0000, v206
	v_lshlrev_b32_e32 v90, 16, v207
	v_and_b32_e32 v91, 0xffff0000, v207
	v_pk_add_f32 v[80:81], v[80:81], v[84:85]
	v_pk_add_f32 v[78:79], v[78:79], v[94:95]
	v_pk_add_f32 v[72:73], v[72:73], v[88:89]
	v_pk_add_f32 v[70:71], v[70:71], v[98:99]
	v_pk_add_f32 v[76:77], v[76:77], v[86:87]
	v_pk_add_f32 v[74:75], v[74:75], v[96:97]
	v_pk_add_f32 v[84:85], v[68:69], v[90:91]
	v_pk_add_f32 v[86:87], v[66:67], v[100:101]
	v_mul_f32_e32 v68, v79, v79
	v_mul_f32_e32 v69, v81, v81
	v_mul_f32_e32 v88, v71, v71
	v_mul_f32_e32 v89, v73, v73
	v_cvt_pk_bf16_f32 v66, v78, v79
	v_mul_f32_e32 v79, v75, v75
	v_mul_f32_e32 v90, v87, v87
	v_fmac_f32_e32 v68, v78, v78
	v_fmac_f32_e32 v69, v80, v80
	v_fmac_f32_e32 v88, v70, v70
	v_fmac_f32_e32 v89, v72, v72
	v_cvt_pk_bf16_f32 v67, v80, v81
	v_mul_f32_e32 v81, v77, v77
	v_mul_f32_e32 v91, v85, v85
	v_fmac_f32_e32 v79, v74, v74
	v_fmac_f32_e32 v90, v86, v86
	v_add_f32_e32 v68, v68, v69
	v_add_f32_e32 v69, v88, v89
	v_fmac_f32_e32 v81, v76, v76
	v_fmac_f32_e32 v91, v84, v84
	v_add_f32_e32 v68, v79, v68
	v_add_f32_e32 v69, v90, v69
	v_add_f32_e32 v68, v81, v68
	v_add_f32_e32 v69, v91, v69
	v_add_f32_e32 v78, v68, v69
	ds_bpermute_b32 v79, v158, v78
	v_cvt_pk_bf16_f32 v68, v74, v75
	v_cvt_pk_bf16_f32 v69, v76, v77
	global_store_dwordx4 v[92:93], v[66:69], off sc0 sc1
	s_waitcnt lgkmcnt(0)
	s_nop 0
	v_add_f32_e32 v66, v78, v79
	ds_bpermute_b32 v67, v157, v66
	v_cvt_pk_bf16_f32 v68, v70, v71
	v_cvt_pk_bf16_f32 v69, v72, v73
	v_cvt_pk_bf16_f32 v70, v86, v87
	v_cvt_pk_bf16_f32 v71, v84, v85
	global_store_dwordx4 v[92:93], v[68:71], off offset:256 sc0 sc1
	s_and_saveexec_b64 s[24:25], s[2:3]
	s_cbranch_execz .LBB0_1615
	v_lshl_add_u64 v[68:69], v[82:83], 2, s[6:7]
	s_waitcnt lgkmcnt(0)
	v_add_f32_e32 v66, v66, v67
	global_atomic_add_f32 v[68:69], v66, off
